# keep_v10 + the two s_waitcnt that end every GEMM load segment merged into one (vmcnt(N) lgkmcnt(0)): one instruction less before the barrier arrival, 36 sites
# speedup vs baseline: 1.0047x; 1.0033x over previous
.LBB0_182:
	s_add_u32 s6, s4, 0xfffc0080
	s_addc_u32 s7, s5, -1
	s_add_i32 s9, 0, 0x10000
	s_cmp_eq_u32 s53, 12
	s_cselect_b32 s27, s39, s7
	s_cselect_b32 s26, s49, s6
	v_add_u32_e32 v0, s9, v189
	s_cselect_b32 s7, s15, s52
	s_cselect_b32 s6, s50, s51
	s_add_i32 s83, 0, 0x14000
	ds_read_b128 v[130:133], v0
	ds_read_b128 v[134:137], v0 offset:1024
	ds_read_b128 v[162:165], v0 offset:2048
	ds_read_b128 v[166:169], v0 offset:3072
	v_add_u32_e32 v0, s83, v189
	ds_read_b128 v[170:173], v0
	ds_read_b128 v[174:177], v0 offset:1024
	ds_read_b128 v[178:181], v0 offset:2048
	ds_read_b128 v[182:185], v0 offset:3072
	v_lshl_add_u64 v[148:149], s[4:5], 0, v[158:159]
	s_add_i32 m0, s40, 0xc000
	ds_read_b128 v[196:199], v193
	ds_read_b128 v[200:203], v193 offset:1024
	ds_read_b128 v[204:207], v193 offset:2048
	ds_read_b128 v[208:211], v193 offset:3072
	ds_read_b128 v[212:215], v193 offset:4096
	ds_read_b128 v[216:219], v193 offset:5120
	ds_read_b128 v[220:223], v193 offset:6144
	ds_read_b128 v[224:227], v193 offset:7168
	global_load_lds_dwordx4 v[148:149], off
	s_add_i32 m0, s40, 0xe000
	v_lshl_add_u64 v[148:149], s[4:5], 0, v[160:161]
	global_load_lds_dwordx4 v[148:149], off
	s_waitcnt vmcnt(8) lgkmcnt(0)
	s_setprio 1
	s_barrier
	v_mfma_f32_16x16x32_bf16 v[126:129], v[130:133], v[196:199], v[126:129]
	v_mfma_f32_16x16x32_bf16 v[122:125], v[162:165], v[196:199], v[122:125]
	v_mfma_f32_16x16x32_bf16 v[118:121], v[130:133], v[204:207], v[118:121]
	v_mfma_f32_16x16x32_bf16 v[114:117], v[162:165], v[204:207], v[114:117]
	v_mfma_f32_16x16x32_bf16 v[102:105], v[130:133], v[212:215], v[102:105]
	v_mfma_f32_16x16x32_bf16 v[98:101], v[162:165], v[212:215], v[98:101]
	v_mfma_f32_16x16x32_bf16 v[86:89], v[130:133], v[220:223], v[86:89]
	v_mfma_f32_16x16x32_bf16 v[82:85], v[162:165], v[220:223], v[82:85]
	v_mfma_f32_16x16x32_bf16 v[126:129], v[134:137], v[200:203], v[126:129]
	v_mfma_f32_16x16x32_bf16 v[122:125], v[166:169], v[200:203], v[122:125]
	v_mfma_f32_16x16x32_bf16 v[118:121], v[134:137], v[208:211], v[118:121]
	v_mfma_f32_16x16x32_bf16 v[114:117], v[166:169], v[208:211], v[114:117]
	v_mfma_f32_16x16x32_bf16 v[102:105], v[134:137], v[216:219], v[102:105]
	v_mfma_f32_16x16x32_bf16 v[98:101], v[166:169], v[216:219], v[98:101]
	v_mfma_f32_16x16x32_bf16 v[86:89], v[134:137], v[224:227], v[86:89]
	v_mfma_f32_16x16x32_bf16 v[82:85], v[166:169], v[224:227], v[82:85]
	v_mfma_f32_16x16x32_bf16 v[110:113], v[170:173], v[196:199], v[110:113]
	v_mfma_f32_16x16x32_bf16 v[106:109], v[178:181], v[196:199], v[106:109]
	v_mfma_f32_16x16x32_bf16 v[94:97], v[170:173], v[204:207], v[94:97]
	v_mfma_f32_16x16x32_bf16 v[90:93], v[178:181], v[204:207], v[90:93]
	v_mfma_f32_16x16x32_bf16 v[78:81], v[170:173], v[212:215], v[78:81]
	v_mfma_f32_16x16x32_bf16 v[74:77], v[178:181], v[212:215], v[74:77]
	v_mfma_f32_16x16x32_bf16 v[70:73], v[170:173], v[220:223], v[70:73]
	v_mfma_f32_16x16x32_bf16 v[66:69], v[178:181], v[220:223], v[66:69]
	v_mfma_f32_16x16x32_bf16 v[110:113], v[174:177], v[200:203], v[110:113]
	v_mfma_f32_16x16x32_bf16 v[106:109], v[182:185], v[200:203], v[106:109]
	v_mfma_f32_16x16x32_bf16 v[94:97], v[174:177], v[208:211], v[94:97]
	v_mfma_f32_16x16x32_bf16 v[90:93], v[182:185], v[208:211], v[90:93]
	v_mfma_f32_16x16x32_bf16 v[78:81], v[174:177], v[216:219], v[78:81]
	v_mfma_f32_16x16x32_bf16 v[74:77], v[182:185], v[216:219], v[74:77]
	v_mfma_f32_16x16x32_bf16 v[70:73], v[174:177], v[224:227], v[70:73]
	v_mfma_f32_16x16x32_bf16 v[66:69], v[182:185], v[224:227], v[66:69]
	s_setprio 0
	s_barrier
	s_add_i32 s9, s9, s29
	v_lshl_add_u64 v[148:149], s[6:7], 0, v[142:143]
	s_mov_b32 m0, s9
	ds_read_b128 v[196:199], v193 offset:16384
	ds_read_b128 v[200:203], v193 offset:17408
	ds_read_b128 v[204:207], v193 offset:18432
	ds_read_b128 v[208:211], v193 offset:19456
	ds_read_b128 v[212:215], v193 offset:20480
	ds_read_b128 v[216:219], v193 offset:21504
	ds_read_b128 v[220:223], v193 offset:22528
	ds_read_b128 v[224:227], v193 offset:23552
	global_load_lds_dwordx4 v[148:149], off
	s_add_i32 m0, s9, 0x2000
	s_add_u32 s78, s6, 0x40000
	v_lshl_add_u64 v[150:151], s[6:7], 0, v[138:139]
	s_addc_u32 s79, s7, 0
	s_add_i32 s9, s83, s29
	global_load_lds_dwordx4 v[150:151], off
	v_lshl_add_u64 v[186:187], s[78:79], 0, v[142:143]
	s_mov_b32 m0, s9
	v_lshl_add_u64 v[228:229], s[26:27], 0, v[140:141]
	global_load_lds_dwordx4 v[186:187], off
	s_add_i32 m0, s9, 0x2000
	v_lshl_add_u64 v[186:187], s[78:79], 0, v[138:139]
	global_load_lds_dwordx4 v[186:187], off
	s_mov_b32 m0, s40
	v_lshl_add_u64 v[186:187], s[26:27], 0, v[144:145]
	global_load_lds_dwordx4 v[186:187], off
	s_mov_b32 m0, s41
	s_nop 0
	global_load_lds_dwordx4 v[228:229], off
	s_waitcnt vmcnt(8) lgkmcnt(0)
	s_setprio 1
	s_barrier
	v_mfma_f32_16x16x32_bf16 v[62:65], v[130:133], v[196:199], v[62:65]
	v_mfma_f32_16x16x32_bf16 v[58:61], v[162:165], v[196:199], v[58:61]
	v_mfma_f32_16x16x32_bf16 v[54:57], v[130:133], v[204:207], v[54:57]
	v_mfma_f32_16x16x32_bf16 v[50:53], v[162:165], v[204:207], v[50:53]
	v_mfma_f32_16x16x32_bf16 v[38:41], v[130:133], v[212:215], v[38:41]
	v_mfma_f32_16x16x32_bf16 v[34:37], v[162:165], v[212:215], v[34:37]
	v_mfma_f32_16x16x32_bf16 v[22:25], v[130:133], v[220:223], v[22:25]
	v_mfma_f32_16x16x32_bf16 v[18:21], v[162:165], v[220:223], v[18:21]
	v_mfma_f32_16x16x32_bf16 v[62:65], v[134:137], v[200:203], v[62:65]
	v_mfma_f32_16x16x32_bf16 v[58:61], v[166:169], v[200:203], v[58:61]
	v_mfma_f32_16x16x32_bf16 v[54:57], v[134:137], v[208:211], v[54:57]
	v_mfma_f32_16x16x32_bf16 v[50:53], v[166:169], v[208:211], v[50:53]
	v_mfma_f32_16x16x32_bf16 v[38:41], v[134:137], v[216:219], v[38:41]
	v_mfma_f32_16x16x32_bf16 v[34:37], v[166:169], v[216:219], v[34:37]
	v_mfma_f32_16x16x32_bf16 v[22:25], v[134:137], v[224:227], v[22:25]
	v_mfma_f32_16x16x32_bf16 v[18:21], v[166:169], v[224:227], v[18:21]
	v_mfma_f32_16x16x32_bf16 v[46:49], v[170:173], v[196:199], v[46:49]
	v_mfma_f32_16x16x32_bf16 v[42:45], v[178:181], v[196:199], v[42:45]
	v_mfma_f32_16x16x32_bf16 v[30:33], v[170:173], v[204:207], v[30:33]
	v_mfma_f32_16x16x32_bf16 v[26:29], v[178:181], v[204:207], v[26:29]
	v_mfma_f32_16x16x32_bf16 v[14:17], v[170:173], v[212:215], v[14:17]
	v_mfma_f32_16x16x32_bf16 v[10:13], v[178:181], v[212:215], v[10:13]
	v_mfma_f32_16x16x32_bf16 v[6:9], v[170:173], v[220:223], v[6:9]
	v_mfma_f32_16x16x32_bf16 v[2:5], v[178:181], v[220:223], v[2:5]
	v_mfma_f32_16x16x32_bf16 v[46:49], v[174:177], v[200:203], v[46:49]
	v_mfma_f32_16x16x32_bf16 v[42:45], v[182:185], v[200:203], v[42:45]
	v_mfma_f32_16x16x32_bf16 v[30:33], v[174:177], v[208:211], v[30:33]
	v_mfma_f32_16x16x32_bf16 v[26:29], v[182:185], v[208:211], v[26:29]
	v_mfma_f32_16x16x32_bf16 v[14:17], v[174:177], v[216:219], v[14:17]
	v_mfma_f32_16x16x32_bf16 v[10:13], v[182:185], v[216:219], v[10:13]
	v_mfma_f32_16x16x32_bf16 v[6:9], v[174:177], v[224:227], v[6:9]
	v_mfma_f32_16x16x32_bf16 v[2:5], v[182:185], v[224:227], v[2:5]
	s_setprio 0
	s_barrier
	s_add_i32 s9, 0, 0x18000
	v_add_u32_e32 v0, s9, v189
	s_add_i32 s78, 0, 0x1c000
	ds_read_b128 v[130:133], v0
	ds_read_b128 v[134:137], v0 offset:1024
	ds_read_b128 v[162:165], v0 offset:2048
	ds_read_b128 v[166:169], v0 offset:3072
	v_add_u32_e32 v0, s78, v189
	ds_read_b128 v[170:173], v0
	ds_read_b128 v[174:177], v0 offset:1024
	ds_read_b128 v[178:181], v0 offset:2048
	ds_read_b128 v[182:185], v0 offset:3072
	s_add_u32 s26, s26, 0x40000
	s_addc_u32 s27, s27, 0
	s_mov_b32 m0, s42
	v_lshl_add_u64 v[230:231], s[26:27], 0, v[144:145]
	ds_read_b128 v[196:199], v193 offset:32768
	ds_read_b128 v[200:203], v193 offset:33792
	ds_read_b128 v[204:207], v193 offset:34816
	ds_read_b128 v[208:211], v193 offset:35840
	ds_read_b128 v[212:215], v193 offset:36864
	ds_read_b128 v[216:219], v193 offset:37888
	ds_read_b128 v[220:223], v193 offset:38912
	ds_read_b128 v[224:227], v193 offset:39936
	global_load_lds_dwordx4 v[230:231], off
	s_mov_b32 m0, s43
	v_lshl_add_u64 v[230:231], s[26:27], 0, v[140:141]
	global_load_lds_dwordx4 v[230:231], off
	s_waitcnt vmcnt(8) lgkmcnt(0)
	s_setprio 1
	s_barrier
	v_mfma_f32_16x16x32_bf16 v[126:129], v[130:133], v[196:199], v[126:129]
	v_mfma_f32_16x16x32_bf16 v[122:125], v[162:165], v[196:199], v[122:125]
	v_mfma_f32_16x16x32_bf16 v[118:121], v[130:133], v[204:207], v[118:121]
	v_mfma_f32_16x16x32_bf16 v[114:117], v[162:165], v[204:207], v[114:117]
	v_mfma_f32_16x16x32_bf16 v[102:105], v[130:133], v[212:215], v[102:105]
	v_mfma_f32_16x16x32_bf16 v[98:101], v[162:165], v[212:215], v[98:101]
	v_mfma_f32_16x16x32_bf16 v[86:89], v[130:133], v[220:223], v[86:89]
	v_mfma_f32_16x16x32_bf16 v[82:85], v[162:165], v[220:223], v[82:85]
	v_mfma_f32_16x16x32_bf16 v[126:129], v[134:137], v[200:203], v[126:129]
	v_mfma_f32_16x16x32_bf16 v[122:125], v[166:169], v[200:203], v[122:125]
	v_mfma_f32_16x16x32_bf16 v[118:121], v[134:137], v[208:211], v[118:121]
	v_mfma_f32_16x16x32_bf16 v[114:117], v[166:169], v[208:211], v[114:117]
	v_mfma_f32_16x16x32_bf16 v[102:105], v[134:137], v[216:219], v[102:105]
	v_mfma_f32_16x16x32_bf16 v[98:101], v[166:169], v[216:219], v[98:101]
	v_mfma_f32_16x16x32_bf16 v[86:89], v[134:137], v[224:227], v[86:89]
	v_mfma_f32_16x16x32_bf16 v[82:85], v[166:169], v[224:227], v[82:85]
	v_mfma_f32_16x16x32_bf16 v[110:113], v[170:173], v[196:199], v[110:113]
	v_mfma_f32_16x16x32_bf16 v[106:109], v[178:181], v[196:199], v[106:109]
	v_mfma_f32_16x16x32_bf16 v[94:97], v[170:173], v[204:207], v[94:97]
	v_mfma_f32_16x16x32_bf16 v[90:93], v[178:181], v[204:207], v[90:93]
	v_mfma_f32_16x16x32_bf16 v[78:81], v[170:173], v[212:215], v[78:81]
	v_mfma_f32_16x16x32_bf16 v[74:77], v[178:181], v[212:215], v[74:77]
	v_mfma_f32_16x16x32_bf16 v[70:73], v[170:173], v[220:223], v[70:73]
	v_mfma_f32_16x16x32_bf16 v[66:69], v[178:181], v[220:223], v[66:69]
	v_mfma_f32_16x16x32_bf16 v[110:113], v[174:177], v[200:203], v[110:113]
	v_mfma_f32_16x16x32_bf16 v[106:109], v[182:185], v[200:203], v[106:109]
	v_mfma_f32_16x16x32_bf16 v[94:97], v[174:177], v[208:211], v[94:97]
	v_mfma_f32_16x16x32_bf16 v[90:93], v[182:185], v[208:211], v[90:93]
	v_mfma_f32_16x16x32_bf16 v[78:81], v[174:177], v[216:219], v[78:81]
	v_mfma_f32_16x16x32_bf16 v[74:77], v[182:185], v[216:219], v[74:77]
	v_mfma_f32_16x16x32_bf16 v[70:73], v[174:177], v[224:227], v[70:73]
	v_mfma_f32_16x16x32_bf16 v[66:69], v[182:185], v[224:227], v[66:69]
	s_setprio 0
	s_barrier
	s_add_i32 s9, s9, s29
	v_lshl_add_u64 v[148:149], v[148:149], 0, s[70:71]
	s_mov_b32 m0, s9
	ds_read_b128 v[196:199], v193 offset:49152
	ds_read_b128 v[200:203], v193 offset:50176
	ds_read_b128 v[204:207], v193 offset:51200
	ds_read_b128 v[208:211], v193 offset:52224
	ds_read_b128 v[212:215], v193 offset:53248
	ds_read_b128 v[216:219], v193 offset:54272
	ds_read_b128 v[220:223], v193 offset:55296
	ds_read_b128 v[224:227], v193 offset:56320
	global_load_lds_dwordx4 v[148:149], off
	s_add_i32 m0, s9, 0x2000
	s_add_u32 s6, s6, 0x40080
	v_lshl_add_u64 v[148:149], v[150:151], 0, s[70:71]
	s_addc_u32 s7, s7, 0
	s_add_i32 s9, s78, s29
	global_load_lds_dwordx4 v[148:149], off
	s_mov_b32 m0, s9
	v_lshl_add_u64 v[148:149], s[6:7], 0, v[142:143]
	global_load_lds_dwordx4 v[148:149], off
	s_add_i32 m0, s9, 0x2000
	v_lshl_add_u64 v[148:149], s[6:7], 0, v[138:139]
	global_load_lds_dwordx4 v[148:149], off
	s_mov_b32 m0, s44
	v_lshl_add_u64 v[148:149], v[186:187], 0, s[70:71]
	global_load_lds_dwordx4 v[148:149], off
	s_mov_b32 m0, s45
	v_lshl_add_u64 v[148:149], v[228:229], 0, s[70:71]
	global_load_lds_dwordx4 v[148:149], off
	s_waitcnt vmcnt(8) lgkmcnt(0)
	s_setprio 1
	s_barrier
	v_mfma_f32_16x16x32_bf16 v[62:65], v[130:133], v[196:199], v[62:65]
	v_mfma_f32_16x16x32_bf16 v[58:61], v[162:165], v[196:199], v[58:61]
	v_mfma_f32_16x16x32_bf16 v[54:57], v[130:133], v[204:207], v[54:57]
	v_mfma_f32_16x16x32_bf16 v[50:53], v[162:165], v[204:207], v[50:53]
	v_mfma_f32_16x16x32_bf16 v[38:41], v[130:133], v[212:215], v[38:41]
	v_mfma_f32_16x16x32_bf16 v[34:37], v[162:165], v[212:215], v[34:37]
	v_mfma_f32_16x16x32_bf16 v[22:25], v[130:133], v[220:223], v[22:25]
	v_mfma_f32_16x16x32_bf16 v[18:21], v[162:165], v[220:223], v[18:21]
	v_mfma_f32_16x16x32_bf16 v[62:65], v[134:137], v[200:203], v[62:65]
	v_mfma_f32_16x16x32_bf16 v[58:61], v[166:169], v[200:203], v[58:61]
	v_mfma_f32_16x16x32_bf16 v[54:57], v[134:137], v[208:211], v[54:57]
	v_mfma_f32_16x16x32_bf16 v[50:53], v[166:169], v[208:211], v[50:53]
	v_mfma_f32_16x16x32_bf16 v[38:41], v[134:137], v[216:219], v[38:41]
	v_mfma_f32_16x16x32_bf16 v[34:37], v[166:169], v[216:219], v[34:37]
	v_mfma_f32_16x16x32_bf16 v[22:25], v[134:137], v[224:227], v[22:25]
	v_mfma_f32_16x16x32_bf16 v[18:21], v[166:169], v[224:227], v[18:21]
	v_mfma_f32_16x16x32_bf16 v[46:49], v[170:173], v[196:199], v[46:49]
	v_mfma_f32_16x16x32_bf16 v[42:45], v[178:181], v[196:199], v[42:45]
	v_mfma_f32_16x16x32_bf16 v[30:33], v[170:173], v[204:207], v[30:33]
	v_mfma_f32_16x16x32_bf16 v[26:29], v[178:181], v[204:207], v[26:29]
	v_mfma_f32_16x16x32_bf16 v[14:17], v[170:173], v[212:215], v[14:17]
	v_mfma_f32_16x16x32_bf16 v[10:13], v[178:181], v[212:215], v[10:13]
	v_mfma_f32_16x16x32_bf16 v[6:9], v[170:173], v[220:223], v[6:9]
	v_mfma_f32_16x16x32_bf16 v[2:5], v[178:181], v[220:223], v[2:5]
	v_mfma_f32_16x16x32_bf16 v[46:49], v[174:177], v[200:203], v[46:49]
	v_mfma_f32_16x16x32_bf16 v[42:45], v[182:185], v[200:203], v[42:45]
	v_mfma_f32_16x16x32_bf16 v[30:33], v[174:177], v[208:211], v[30:33]
	v_mfma_f32_16x16x32_bf16 v[26:29], v[182:185], v[208:211], v[26:29]
	v_mfma_f32_16x16x32_bf16 v[14:17], v[174:177], v[216:219], v[14:17]
	v_mfma_f32_16x16x32_bf16 v[10:13], v[182:185], v[216:219], v[10:13]
	v_mfma_f32_16x16x32_bf16 v[6:9], v[174:177], v[224:227], v[6:9]
	v_mfma_f32_16x16x32_bf16 v[2:5], v[182:185], v[224:227], v[2:5]
	s_setprio 0
	s_barrier
	s_add_i32 s53, s53, 2
	s_add_u32 s4, s4, 0x100
	s_addc_u32 s5, s5, 0
	s_add_u32 s51, s51, 0x100
	s_addc_u32 s52, s52, 0
	s_cmp_gt_u32 s53, 13
	s_cbranch_scc0 .LBB0_182
	s_and_b64 vcc, exec, s[36:37]
	s_cbranch_vccz .LBB0_185
	s_barrier

.LBB0_220:
	s_add_u32 s9, s36, 0xfffc0080
	s_addc_u32 s26, s37, -1
	s_add_i32 s60, 0, 0x10000
	s_cmp_eq_u32 s53, 12
	s_cselect_b32 s39, s19, s26
	s_cselect_b32 s38, s49, s9
	v_add_u32_e32 v148, s60, v141
	s_cselect_b32 s27, s17, s52
	s_cselect_b32 s26, s50, s51
	s_add_i32 s9, 0, 0x14000
	ds_read_b128 v[144:147], v148
	ds_read_b128 v[156:159], v148 offset:1024
	ds_read_b128 v[160:163], v148 offset:2048
	ds_read_b128 v[164:167], v148 offset:3072
	v_add_u32_e32 v148, s9, v141
	ds_read_b128 v[168:171], v148
	ds_read_b128 v[172:175], v148 offset:1024
	ds_read_b128 v[176:179], v148 offset:2048
	ds_read_b128 v[180:183], v148 offset:3072
	v_lshl_add_u64 v[148:149], s[36:37], 0, v[136:137]
	s_add_i32 m0, s40, 0xc000
	ds_read_b128 v[184:187], v143
	ds_read_b128 v[188:191], v143 offset:1024
	ds_read_b128 v[192:195], v143 offset:2048
	ds_read_b128 v[196:199], v143 offset:3072
	ds_read_b128 v[200:203], v143 offset:4096
	ds_read_b128 v[204:207], v143 offset:5120
	ds_read_b128 v[208:211], v143 offset:6144
	ds_read_b128 v[212:215], v143 offset:7168
	global_load_lds_dwordx4 v[148:149], off
	s_add_i32 m0, s40, 0xe000
	v_lshl_add_u64 v[148:149], s[36:37], 0, v[138:139]
	global_load_lds_dwordx4 v[148:149], off
	s_waitcnt vmcnt(8) lgkmcnt(0)
	s_setprio 1
	s_barrier
	v_mfma_f32_16x16x32_bf16 v[126:129], v[144:147], v[184:187], v[126:129]
	v_mfma_f32_16x16x32_bf16 v[122:125], v[160:163], v[184:187], v[122:125]
	v_mfma_f32_16x16x32_bf16 v[118:121], v[144:147], v[192:195], v[118:121]
	v_mfma_f32_16x16x32_bf16 v[114:117], v[160:163], v[192:195], v[114:117]
	v_mfma_f32_16x16x32_bf16 v[102:105], v[144:147], v[200:203], v[102:105]
	v_mfma_f32_16x16x32_bf16 v[98:101], v[160:163], v[200:203], v[98:101]
	v_mfma_f32_16x16x32_bf16 v[86:89], v[144:147], v[208:211], v[86:89]
	v_mfma_f32_16x16x32_bf16 v[82:85], v[160:163], v[208:211], v[82:85]
	v_mfma_f32_16x16x32_bf16 v[126:129], v[156:159], v[188:191], v[126:129]
	v_mfma_f32_16x16x32_bf16 v[122:125], v[164:167], v[188:191], v[122:125]
	v_mfma_f32_16x16x32_bf16 v[118:121], v[156:159], v[196:199], v[118:121]
	v_mfma_f32_16x16x32_bf16 v[114:117], v[164:167], v[196:199], v[114:117]
	v_mfma_f32_16x16x32_bf16 v[102:105], v[156:159], v[204:207], v[102:105]
	v_mfma_f32_16x16x32_bf16 v[98:101], v[164:167], v[204:207], v[98:101]
	v_mfma_f32_16x16x32_bf16 v[86:89], v[156:159], v[212:215], v[86:89]
	v_mfma_f32_16x16x32_bf16 v[82:85], v[164:167], v[212:215], v[82:85]
	v_mfma_f32_16x16x32_bf16 v[110:113], v[168:171], v[184:187], v[110:113]
	v_mfma_f32_16x16x32_bf16 v[106:109], v[176:179], v[184:187], v[106:109]
	v_mfma_f32_16x16x32_bf16 v[94:97], v[168:171], v[192:195], v[94:97]
	v_mfma_f32_16x16x32_bf16 v[90:93], v[176:179], v[192:195], v[90:93]
	v_mfma_f32_16x16x32_bf16 v[78:81], v[168:171], v[200:203], v[78:81]
	v_mfma_f32_16x16x32_bf16 v[74:77], v[176:179], v[200:203], v[74:77]
	v_mfma_f32_16x16x32_bf16 v[70:73], v[168:171], v[208:211], v[70:73]
	v_mfma_f32_16x16x32_bf16 v[66:69], v[176:179], v[208:211], v[66:69]
	v_mfma_f32_16x16x32_bf16 v[110:113], v[172:175], v[188:191], v[110:113]
	v_mfma_f32_16x16x32_bf16 v[106:109], v[180:183], v[188:191], v[106:109]
	v_mfma_f32_16x16x32_bf16 v[94:97], v[172:175], v[196:199], v[94:97]
	v_mfma_f32_16x16x32_bf16 v[90:93], v[180:183], v[196:199], v[90:93]
	v_mfma_f32_16x16x32_bf16 v[78:81], v[172:175], v[204:207], v[78:81]
	v_mfma_f32_16x16x32_bf16 v[74:77], v[180:183], v[204:207], v[74:77]
	v_mfma_f32_16x16x32_bf16 v[70:73], v[172:175], v[212:215], v[70:73]
	v_mfma_f32_16x16x32_bf16 v[66:69], v[180:183], v[212:215], v[66:69]
	s_setprio 0
	s_barrier
	s_add_i32 s60, s60, s29
	v_lshl_add_u64 v[148:149], s[26:27], 0, v[0:1]
	s_mov_b32 m0, s60
	ds_read_b128 v[184:187], v143 offset:16384
	ds_read_b128 v[188:191], v143 offset:17408
	ds_read_b128 v[192:195], v143 offset:18432
	ds_read_b128 v[196:199], v143 offset:19456
	ds_read_b128 v[200:203], v143 offset:20480
	ds_read_b128 v[204:207], v143 offset:21504
	ds_read_b128 v[208:211], v143 offset:22528
	ds_read_b128 v[212:215], v143 offset:23552
	global_load_lds_dwordx4 v[148:149], off
	s_add_i32 m0, s60, 0x2000
	s_add_u32 s60, s26, 0x40000
	v_lshl_add_u64 v[150:151], s[26:27], 0, v[130:131]
	s_addc_u32 s61, s27, 0
	s_add_i32 s9, s9, s29
	global_load_lds_dwordx4 v[150:151], off
	v_lshl_add_u64 v[216:217], s[60:61], 0, v[0:1]
	s_mov_b32 m0, s9
	v_lshl_add_u64 v[218:219], s[38:39], 0, v[132:133]
	global_load_lds_dwordx4 v[216:217], off
	s_add_i32 m0, s9, 0x2000
	v_lshl_add_u64 v[216:217], s[60:61], 0, v[130:131]
	global_load_lds_dwordx4 v[216:217], off
	s_mov_b32 m0, s40
	v_lshl_add_u64 v[216:217], s[38:39], 0, v[134:135]
	global_load_lds_dwordx4 v[216:217], off
	s_mov_b32 m0, s41
	s_nop 0
	global_load_lds_dwordx4 v[218:219], off
	s_waitcnt vmcnt(8) lgkmcnt(0)
	s_setprio 1
	s_barrier
	v_mfma_f32_16x16x32_bf16 v[62:65], v[144:147], v[184:187], v[62:65]
	v_mfma_f32_16x16x32_bf16 v[58:61], v[160:163], v[184:187], v[58:61]
	v_mfma_f32_16x16x32_bf16 v[54:57], v[144:147], v[192:195], v[54:57]
	v_mfma_f32_16x16x32_bf16 v[50:53], v[160:163], v[192:195], v[50:53]
	v_mfma_f32_16x16x32_bf16 v[38:41], v[144:147], v[200:203], v[38:41]
	v_mfma_f32_16x16x32_bf16 v[34:37], v[160:163], v[200:203], v[34:37]
	v_mfma_f32_16x16x32_bf16 v[22:25], v[144:147], v[208:211], v[22:25]
	v_mfma_f32_16x16x32_bf16 v[18:21], v[160:163], v[208:211], v[18:21]
	v_mfma_f32_16x16x32_bf16 v[62:65], v[156:159], v[188:191], v[62:65]
	v_mfma_f32_16x16x32_bf16 v[58:61], v[164:167], v[188:191], v[58:61]
	v_mfma_f32_16x16x32_bf16 v[54:57], v[156:159], v[196:199], v[54:57]
	v_mfma_f32_16x16x32_bf16 v[50:53], v[164:167], v[196:199], v[50:53]
	v_mfma_f32_16x16x32_bf16 v[38:41], v[156:159], v[204:207], v[38:41]
	v_mfma_f32_16x16x32_bf16 v[34:37], v[164:167], v[204:207], v[34:37]
	v_mfma_f32_16x16x32_bf16 v[22:25], v[156:159], v[212:215], v[22:25]
	v_mfma_f32_16x16x32_bf16 v[18:21], v[164:167], v[212:215], v[18:21]
	v_mfma_f32_16x16x32_bf16 v[46:49], v[168:171], v[184:187], v[46:49]
	v_mfma_f32_16x16x32_bf16 v[42:45], v[176:179], v[184:187], v[42:45]
	v_mfma_f32_16x16x32_bf16 v[30:33], v[168:171], v[192:195], v[30:33]
	v_mfma_f32_16x16x32_bf16 v[26:29], v[176:179], v[192:195], v[26:29]
	v_mfma_f32_16x16x32_bf16 v[14:17], v[168:171], v[200:203], v[14:17]
	v_mfma_f32_16x16x32_bf16 v[10:13], v[176:179], v[200:203], v[10:13]
	v_mfma_f32_16x16x32_bf16 v[6:9], v[168:171], v[208:211], v[6:9]
	v_mfma_f32_16x16x32_bf16 v[2:5], v[176:179], v[208:211], v[2:5]
	v_mfma_f32_16x16x32_bf16 v[46:49], v[172:175], v[188:191], v[46:49]
	v_mfma_f32_16x16x32_bf16 v[42:45], v[180:183], v[188:191], v[42:45]
	v_mfma_f32_16x16x32_bf16 v[30:33], v[172:175], v[196:199], v[30:33]
	v_mfma_f32_16x16x32_bf16 v[26:29], v[180:183], v[196:199], v[26:29]
	v_mfma_f32_16x16x32_bf16 v[14:17], v[172:175], v[204:207], v[14:17]
	v_mfma_f32_16x16x32_bf16 v[10:13], v[180:183], v[204:207], v[10:13]
	v_mfma_f32_16x16x32_bf16 v[6:9], v[172:175], v[212:215], v[6:9]
	v_mfma_f32_16x16x32_bf16 v[2:5], v[180:183], v[212:215], v[2:5]
	s_setprio 0
	s_barrier
	s_add_i32 s9, 0, 0x18000
	s_add_i32 s60, 0, 0x1c000
	v_add_u32_e32 v164, s9, v141
	v_add_u32_e32 v180, s60, v141
	ds_read_b128 v[144:147], v164
	ds_read_b128 v[156:159], v164 offset:1024
	ds_read_b128 v[160:163], v164 offset:2048
	ds_read_b128 v[164:167], v164 offset:3072
	ds_read_b128 v[168:171], v180
	ds_read_b128 v[172:175], v180 offset:1024
	ds_read_b128 v[176:179], v180 offset:2048
	ds_read_b128 v[180:183], v180 offset:3072
	s_add_u32 s38, s38, 0x40000
	s_addc_u32 s39, s39, 0
	s_mov_b32 m0, s42
	v_lshl_add_u64 v[220:221], s[38:39], 0, v[134:135]
	ds_read_b128 v[184:187], v143 offset:32768
	ds_read_b128 v[188:191], v143 offset:33792
	ds_read_b128 v[192:195], v143 offset:34816
	ds_read_b128 v[196:199], v143 offset:35840
	ds_read_b128 v[200:203], v143 offset:36864
	ds_read_b128 v[204:207], v143 offset:37888
	ds_read_b128 v[208:211], v143 offset:38912
	ds_read_b128 v[212:215], v143 offset:39936
	global_load_lds_dwordx4 v[220:221], off
	s_mov_b32 m0, s43
	v_lshl_add_u64 v[220:221], s[38:39], 0, v[132:133]
	global_load_lds_dwordx4 v[220:221], off
	s_waitcnt vmcnt(8) lgkmcnt(0)
	s_setprio 1
	s_barrier
	v_mfma_f32_16x16x32_bf16 v[126:129], v[144:147], v[184:187], v[126:129]
	v_mfma_f32_16x16x32_bf16 v[122:125], v[160:163], v[184:187], v[122:125]
	v_mfma_f32_16x16x32_bf16 v[118:121], v[144:147], v[192:195], v[118:121]
	v_mfma_f32_16x16x32_bf16 v[114:117], v[160:163], v[192:195], v[114:117]
	v_mfma_f32_16x16x32_bf16 v[102:105], v[144:147], v[200:203], v[102:105]
	v_mfma_f32_16x16x32_bf16 v[98:101], v[160:163], v[200:203], v[98:101]
	v_mfma_f32_16x16x32_bf16 v[86:89], v[144:147], v[208:211], v[86:89]
	v_mfma_f32_16x16x32_bf16 v[82:85], v[160:163], v[208:211], v[82:85]
	v_mfma_f32_16x16x32_bf16 v[126:129], v[156:159], v[188:191], v[126:129]
	v_mfma_f32_16x16x32_bf16 v[122:125], v[164:167], v[188:191], v[122:125]
	v_mfma_f32_16x16x32_bf16 v[118:121], v[156:159], v[196:199], v[118:121]
	v_mfma_f32_16x16x32_bf16 v[114:117], v[164:167], v[196:199], v[114:117]
	v_mfma_f32_16x16x32_bf16 v[102:105], v[156:159], v[204:207], v[102:105]
	v_mfma_f32_16x16x32_bf16 v[98:101], v[164:167], v[204:207], v[98:101]
	v_mfma_f32_16x16x32_bf16 v[86:89], v[156:159], v[212:215], v[86:89]
	v_mfma_f32_16x16x32_bf16 v[82:85], v[164:167], v[212:215], v[82:85]
	v_mfma_f32_16x16x32_bf16 v[110:113], v[168:171], v[184:187], v[110:113]
	v_mfma_f32_16x16x32_bf16 v[106:109], v[176:179], v[184:187], v[106:109]
	v_mfma_f32_16x16x32_bf16 v[94:97], v[168:171], v[192:195], v[94:97]
	v_mfma_f32_16x16x32_bf16 v[90:93], v[176:179], v[192:195], v[90:93]
	v_mfma_f32_16x16x32_bf16 v[78:81], v[168:171], v[200:203], v[78:81]
	v_mfma_f32_16x16x32_bf16 v[74:77], v[176:179], v[200:203], v[74:77]
	v_mfma_f32_16x16x32_bf16 v[70:73], v[168:171], v[208:211], v[70:73]
	v_mfma_f32_16x16x32_bf16 v[66:69], v[176:179], v[208:211], v[66:69]
	v_mfma_f32_16x16x32_bf16 v[110:113], v[172:175], v[188:191], v[110:113]
	v_mfma_f32_16x16x32_bf16 v[106:109], v[180:183], v[188:191], v[106:109]
	v_mfma_f32_16x16x32_bf16 v[94:97], v[172:175], v[196:199], v[94:97]
	v_mfma_f32_16x16x32_bf16 v[90:93], v[180:183], v[196:199], v[90:93]
	v_mfma_f32_16x16x32_bf16 v[78:81], v[172:175], v[204:207], v[78:81]
	v_mfma_f32_16x16x32_bf16 v[74:77], v[180:183], v[204:207], v[74:77]
	v_mfma_f32_16x16x32_bf16 v[70:73], v[172:175], v[212:215], v[70:73]
	v_mfma_f32_16x16x32_bf16 v[66:69], v[180:183], v[212:215], v[66:69]
	s_setprio 0
	s_barrier
	s_add_i32 s9, s9, s29
	v_lshl_add_u64 v[148:149], v[148:149], 0, s[70:71]
	s_mov_b32 m0, s9
	ds_read_b128 v[184:187], v143 offset:49152
	ds_read_b128 v[188:191], v143 offset:50176
	ds_read_b128 v[192:195], v143 offset:51200
	ds_read_b128 v[196:199], v143 offset:52224
	ds_read_b128 v[200:203], v143 offset:53248
	ds_read_b128 v[204:207], v143 offset:54272
	ds_read_b128 v[208:211], v143 offset:55296
	ds_read_b128 v[212:215], v143 offset:56320
	global_load_lds_dwordx4 v[148:149], off
	s_add_i32 m0, s9, 0x2000
	s_add_u32 s26, s26, 0x40080
	v_lshl_add_u64 v[148:149], v[150:151], 0, s[70:71]
	s_addc_u32 s27, s27, 0
	s_add_i32 s9, s60, s29
	global_load_lds_dwordx4 v[148:149], off
	s_mov_b32 m0, s9
	v_lshl_add_u64 v[148:149], s[26:27], 0, v[0:1]
	global_load_lds_dwordx4 v[148:149], off
	s_add_i32 m0, s9, 0x2000
	v_lshl_add_u64 v[148:149], s[26:27], 0, v[130:131]
	global_load_lds_dwordx4 v[148:149], off
	s_mov_b32 m0, s44
	v_lshl_add_u64 v[148:149], v[216:217], 0, s[70:71]
	global_load_lds_dwordx4 v[148:149], off
	s_mov_b32 m0, s45
	v_lshl_add_u64 v[148:149], v[218:219], 0, s[70:71]
	global_load_lds_dwordx4 v[148:149], off
	s_waitcnt vmcnt(8) lgkmcnt(0)
	s_setprio 1
	s_barrier
	v_mfma_f32_16x16x32_bf16 v[62:65], v[144:147], v[184:187], v[62:65]
	v_mfma_f32_16x16x32_bf16 v[58:61], v[160:163], v[184:187], v[58:61]
	v_mfma_f32_16x16x32_bf16 v[54:57], v[144:147], v[192:195], v[54:57]
	v_mfma_f32_16x16x32_bf16 v[50:53], v[160:163], v[192:195], v[50:53]
	v_mfma_f32_16x16x32_bf16 v[38:41], v[144:147], v[200:203], v[38:41]
	v_mfma_f32_16x16x32_bf16 v[34:37], v[160:163], v[200:203], v[34:37]
	v_mfma_f32_16x16x32_bf16 v[22:25], v[144:147], v[208:211], v[22:25]
	v_mfma_f32_16x16x32_bf16 v[18:21], v[160:163], v[208:211], v[18:21]
	v_mfma_f32_16x16x32_bf16 v[62:65], v[156:159], v[188:191], v[62:65]
	v_mfma_f32_16x16x32_bf16 v[58:61], v[164:167], v[188:191], v[58:61]
	v_mfma_f32_16x16x32_bf16 v[54:57], v[156:159], v[196:199], v[54:57]
	v_mfma_f32_16x16x32_bf16 v[50:53], v[164:167], v[196:199], v[50:53]
	v_mfma_f32_16x16x32_bf16 v[38:41], v[156:159], v[204:207], v[38:41]
	v_mfma_f32_16x16x32_bf16 v[34:37], v[164:167], v[204:207], v[34:37]
	v_mfma_f32_16x16x32_bf16 v[22:25], v[156:159], v[212:215], v[22:25]
	v_mfma_f32_16x16x32_bf16 v[18:21], v[164:167], v[212:215], v[18:21]
	v_mfma_f32_16x16x32_bf16 v[46:49], v[168:171], v[184:187], v[46:49]
	v_mfma_f32_16x16x32_bf16 v[42:45], v[176:179], v[184:187], v[42:45]
	v_mfma_f32_16x16x32_bf16 v[30:33], v[168:171], v[192:195], v[30:33]
	v_mfma_f32_16x16x32_bf16 v[26:29], v[176:179], v[192:195], v[26:29]
	v_mfma_f32_16x16x32_bf16 v[14:17], v[168:171], v[200:203], v[14:17]
	v_mfma_f32_16x16x32_bf16 v[10:13], v[176:179], v[200:203], v[10:13]
	v_mfma_f32_16x16x32_bf16 v[6:9], v[168:171], v[208:211], v[6:9]
	v_mfma_f32_16x16x32_bf16 v[2:5], v[176:179], v[208:211], v[2:5]
	v_mfma_f32_16x16x32_bf16 v[46:49], v[172:175], v[188:191], v[46:49]
	v_mfma_f32_16x16x32_bf16 v[42:45], v[180:183], v[188:191], v[42:45]
	v_mfma_f32_16x16x32_bf16 v[30:33], v[172:175], v[196:199], v[30:33]
	v_mfma_f32_16x16x32_bf16 v[26:29], v[180:183], v[196:199], v[26:29]
	v_mfma_f32_16x16x32_bf16 v[14:17], v[172:175], v[204:207], v[14:17]
	v_mfma_f32_16x16x32_bf16 v[10:13], v[180:183], v[204:207], v[10:13]
	v_mfma_f32_16x16x32_bf16 v[6:9], v[172:175], v[212:215], v[6:9]
	v_mfma_f32_16x16x32_bf16 v[2:5], v[180:183], v[212:215], v[2:5]
	s_setprio 0
	s_barrier
	s_add_i32 s53, s53, 2
	s_add_u32 s36, s36, 0x100
	s_addc_u32 s37, s37, 0
	s_add_u32 s51, s51, 0x100
	s_addc_u32 s52, s52, 0
	s_cmp_gt_u32 s53, 13
	s_cbranch_scc0 .LBB0_220
	s_and_b64 vcc, exec, s[14:15]
	s_cbranch_vccz .LBB0_223
	s_barrier

.LBB0_376:
	s_add_u32 s53, s18, s9
	s_addc_u32 s74, s19, 0
	s_add_u32 s60, s53, 0x100
	s_addc_u32 s61, s74, 0
	s_and_b64 s[26:27], s[38:39], exec
	s_cselect_b32 s61, s25, s61
	s_cselect_b32 s60, s24, s60
	s_add_u32 s9, s16, s9
	s_addc_u32 s26, s17, 0
	s_add_u32 s9, s9, 0x100
	s_addc_u32 s72, s26, 0
	s_add_i32 s92, 0, 0x10000
	s_and_b64 s[26:27], s[38:39], exec
	s_cselect_b32 s73, s23, s72
	s_cselect_b32 s72, s52, s9
	s_add_i32 s39, 0, 0x14000
	s_add_u32 vcc_lo, s53, 0x58080
	s_addc_u32 vcc_hi, s74, 0
	s_add_i32 s78, s92, s41
	s_add_i32 m0, s42, 0xc000
	s_add_i32 s93, s42, 0xe000
	s_add_i32 s91, s78, 0x2000
	v_add_u32_e32 v148, s92, v137
	s_add_u32 s74, s72, 0x10000
	ds_read_b128 v[140:143], v148
	ds_read_b128 v[144:147], v148 offset:1024
	ds_read_b128 v[156:159], v148 offset:2048
	ds_read_b128 v[160:163], v148 offset:3072
	v_add_u32_e32 v148, s39, v137
	s_addc_u32 s75, s73, 0
	s_add_i32 s79, s39, s41
	ds_read_b128 v[164:167], v148
	ds_read_b128 v[168:171], v148 offset:1024
	ds_read_b128 v[172:175], v148 offset:2048
	ds_read_b128 v[176:179], v148 offset:3072
	s_add_i32 s90, s79, 0x2000
	s_add_i32 s97, 0, 0x18000
	s_add_i32 s83, 0, 0x1c000
	s_add_u32 s26, s60, 0x58000
	s_addc_u32 s27, s61, 0
	s_add_i32 s53, s97, s41
	s_add_i32 s9, s53, 0x2000
	s_add_u32 s38, s72, 0x10080
	s_addc_u32 s39, s73, 0
	s_add_i32 s96, s83, s41
	s_add_i32 s92, s96, 0x2000
	v_lshl_add_u64 v[148:149], vcc, 0, v[134:135]
	ds_read_b128 v[180:183], v139
	ds_read_b128 v[184:187], v139 offset:1024
	ds_read_b128 v[188:191], v139 offset:2048
	ds_read_b128 v[192:195], v139 offset:3072
	ds_read_b128 v[196:199], v139 offset:4096
	ds_read_b128 v[200:203], v139 offset:5120
	ds_read_b128 v[204:207], v139 offset:6144
	ds_read_b128 v[208:211], v139 offset:7168
	global_load_lds_dwordx4 v[148:149], off
	s_mov_b32 m0, s93
	v_lshl_add_u64 v[148:149], vcc, 0, v[132:133]
	global_load_lds_dwordx4 v[148:149], off
	s_waitcnt vmcnt(8) lgkmcnt(0)
	s_setprio 1
	s_barrier
	v_mfma_f32_16x16x32_bf16 v[126:129], v[140:143], v[180:183], v[126:129]
	v_mfma_f32_16x16x32_bf16 v[122:125], v[156:159], v[180:183], v[122:125]
	v_mfma_f32_16x16x32_bf16 v[118:121], v[140:143], v[188:191], v[118:121]
	v_mfma_f32_16x16x32_bf16 v[114:117], v[156:159], v[188:191], v[114:117]
	v_mfma_f32_16x16x32_bf16 v[102:105], v[140:143], v[196:199], v[102:105]
	v_mfma_f32_16x16x32_bf16 v[98:101], v[156:159], v[196:199], v[98:101]
	v_mfma_f32_16x16x32_bf16 v[86:89], v[140:143], v[204:207], v[86:89]
	v_mfma_f32_16x16x32_bf16 v[82:85], v[156:159], v[204:207], v[82:85]
	v_mfma_f32_16x16x32_bf16 v[126:129], v[144:147], v[184:187], v[126:129]
	v_mfma_f32_16x16x32_bf16 v[122:125], v[160:163], v[184:187], v[122:125]
	v_mfma_f32_16x16x32_bf16 v[118:121], v[144:147], v[192:195], v[118:121]
	v_mfma_f32_16x16x32_bf16 v[114:117], v[160:163], v[192:195], v[114:117]
	v_mfma_f32_16x16x32_bf16 v[102:105], v[144:147], v[200:203], v[102:105]
	v_mfma_f32_16x16x32_bf16 v[98:101], v[160:163], v[200:203], v[98:101]
	v_mfma_f32_16x16x32_bf16 v[86:89], v[144:147], v[208:211], v[86:89]
	v_mfma_f32_16x16x32_bf16 v[82:85], v[160:163], v[208:211], v[82:85]
	v_mfma_f32_16x16x32_bf16 v[110:113], v[164:167], v[180:183], v[110:113]
	v_mfma_f32_16x16x32_bf16 v[106:109], v[172:175], v[180:183], v[106:109]
	v_mfma_f32_16x16x32_bf16 v[94:97], v[164:167], v[188:191], v[94:97]
	v_mfma_f32_16x16x32_bf16 v[90:93], v[172:175], v[188:191], v[90:93]
	v_mfma_f32_16x16x32_bf16 v[78:81], v[164:167], v[196:199], v[78:81]
	v_mfma_f32_16x16x32_bf16 v[74:77], v[172:175], v[196:199], v[74:77]
	v_mfma_f32_16x16x32_bf16 v[70:73], v[164:167], v[204:207], v[70:73]
	v_mfma_f32_16x16x32_bf16 v[66:69], v[172:175], v[204:207], v[66:69]
	v_mfma_f32_16x16x32_bf16 v[110:113], v[168:171], v[184:187], v[110:113]
	v_mfma_f32_16x16x32_bf16 v[106:109], v[176:179], v[184:187], v[106:109]
	v_mfma_f32_16x16x32_bf16 v[94:97], v[168:171], v[192:195], v[94:97]
	v_mfma_f32_16x16x32_bf16 v[90:93], v[176:179], v[192:195], v[90:93]
	v_mfma_f32_16x16x32_bf16 v[78:81], v[168:171], v[200:203], v[78:81]
	v_mfma_f32_16x16x32_bf16 v[74:77], v[176:179], v[200:203], v[74:77]
	v_mfma_f32_16x16x32_bf16 v[70:73], v[168:171], v[208:211], v[70:73]
	v_mfma_f32_16x16x32_bf16 v[66:69], v[176:179], v[208:211], v[66:69]
	s_setprio 0
	s_barrier
	s_mov_b32 m0, s78
	v_lshl_add_u64 v[148:149], s[72:73], 0, v[0:1]
	ds_read_b128 v[180:183], v139 offset:16384
	ds_read_b128 v[184:187], v139 offset:17408
	ds_read_b128 v[188:191], v139 offset:18432
	ds_read_b128 v[192:195], v139 offset:19456
	ds_read_b128 v[196:199], v139 offset:20480
	ds_read_b128 v[200:203], v139 offset:21504
	ds_read_b128 v[204:207], v139 offset:22528
	ds_read_b128 v[208:211], v139 offset:23552
	global_load_lds_dwordx4 v[148:149], off
	v_lshl_add_u64 v[150:151], s[72:73], 0, v[130:131]
	s_mov_b32 m0, s91
	v_lshl_add_u64 v[212:213], s[74:75], 0, v[0:1]
	global_load_lds_dwordx4 v[150:151], off
	s_mov_b32 m0, s79
	v_lshl_add_u64 v[214:215], s[60:61], 0, v[132:133]
	global_load_lds_dwordx4 v[212:213], off
	s_mov_b32 m0, s90
	v_lshl_add_u64 v[212:213], s[74:75], 0, v[130:131]
	global_load_lds_dwordx4 v[212:213], off
	s_mov_b32 m0, s42
	v_lshl_add_u64 v[212:213], s[60:61], 0, v[134:135]
	global_load_lds_dwordx4 v[212:213], off
	s_mov_b32 m0, s43
	s_nop 0
	global_load_lds_dwordx4 v[214:215], off
	s_waitcnt vmcnt(8) lgkmcnt(0)
	s_setprio 1
	s_barrier
	v_mfma_f32_16x16x32_bf16 v[62:65], v[140:143], v[180:183], v[62:65]
	v_mfma_f32_16x16x32_bf16 v[58:61], v[156:159], v[180:183], v[58:61]
	v_mfma_f32_16x16x32_bf16 v[54:57], v[140:143], v[188:191], v[54:57]
	v_mfma_f32_16x16x32_bf16 v[50:53], v[156:159], v[188:191], v[50:53]
	v_mfma_f32_16x16x32_bf16 v[38:41], v[140:143], v[196:199], v[38:41]
	v_mfma_f32_16x16x32_bf16 v[34:37], v[156:159], v[196:199], v[34:37]
	v_mfma_f32_16x16x32_bf16 v[22:25], v[140:143], v[204:207], v[22:25]
	v_mfma_f32_16x16x32_bf16 v[18:21], v[156:159], v[204:207], v[18:21]
	v_mfma_f32_16x16x32_bf16 v[62:65], v[144:147], v[184:187], v[62:65]
	v_mfma_f32_16x16x32_bf16 v[58:61], v[160:163], v[184:187], v[58:61]
	v_mfma_f32_16x16x32_bf16 v[54:57], v[144:147], v[192:195], v[54:57]
	v_mfma_f32_16x16x32_bf16 v[50:53], v[160:163], v[192:195], v[50:53]
	v_mfma_f32_16x16x32_bf16 v[38:41], v[144:147], v[200:203], v[38:41]
	v_mfma_f32_16x16x32_bf16 v[34:37], v[160:163], v[200:203], v[34:37]
	v_mfma_f32_16x16x32_bf16 v[22:25], v[144:147], v[208:211], v[22:25]
	v_mfma_f32_16x16x32_bf16 v[18:21], v[160:163], v[208:211], v[18:21]
	v_mfma_f32_16x16x32_bf16 v[46:49], v[164:167], v[180:183], v[46:49]
	v_mfma_f32_16x16x32_bf16 v[42:45], v[172:175], v[180:183], v[42:45]
	v_mfma_f32_16x16x32_bf16 v[30:33], v[164:167], v[188:191], v[30:33]
	v_mfma_f32_16x16x32_bf16 v[26:29], v[172:175], v[188:191], v[26:29]
	v_mfma_f32_16x16x32_bf16 v[14:17], v[164:167], v[196:199], v[14:17]
	v_mfma_f32_16x16x32_bf16 v[10:13], v[172:175], v[196:199], v[10:13]
	v_mfma_f32_16x16x32_bf16 v[6:9], v[164:167], v[204:207], v[6:9]
	v_mfma_f32_16x16x32_bf16 v[2:5], v[172:175], v[204:207], v[2:5]
	v_mfma_f32_16x16x32_bf16 v[46:49], v[168:171], v[184:187], v[46:49]
	v_mfma_f32_16x16x32_bf16 v[42:45], v[176:179], v[184:187], v[42:45]
	v_mfma_f32_16x16x32_bf16 v[30:33], v[168:171], v[192:195], v[30:33]
	v_mfma_f32_16x16x32_bf16 v[26:29], v[176:179], v[192:195], v[26:29]
	v_mfma_f32_16x16x32_bf16 v[14:17], v[168:171], v[200:203], v[14:17]
	v_mfma_f32_16x16x32_bf16 v[10:13], v[176:179], v[200:203], v[10:13]
	v_mfma_f32_16x16x32_bf16 v[6:9], v[168:171], v[208:211], v[6:9]
	v_mfma_f32_16x16x32_bf16 v[2:5], v[176:179], v[208:211], v[2:5]
	s_setprio 0
	s_barrier
	v_add_u32_e32 v160, s97, v137
	v_add_u32_e32 v176, s83, v137
	ds_read_b128 v[140:143], v160
	ds_read_b128 v[144:147], v160 offset:1024
	ds_read_b128 v[156:159], v160 offset:2048
	ds_read_b128 v[160:163], v160 offset:3072
	ds_read_b128 v[164:167], v176
	ds_read_b128 v[168:171], v176 offset:1024
	ds_read_b128 v[172:175], v176 offset:2048
	ds_read_b128 v[176:179], v176 offset:3072
	s_mov_b32 m0, s44
	v_lshl_add_u64 v[216:217], s[26:27], 0, v[134:135]
	ds_read_b128 v[180:183], v139 offset:32768
	ds_read_b128 v[184:187], v139 offset:33792
	ds_read_b128 v[188:191], v139 offset:34816
	ds_read_b128 v[192:195], v139 offset:35840
	ds_read_b128 v[196:199], v139 offset:36864
	ds_read_b128 v[200:203], v139 offset:37888
	ds_read_b128 v[204:207], v139 offset:38912
	ds_read_b128 v[208:211], v139 offset:39936
	global_load_lds_dwordx4 v[216:217], off
	s_mov_b32 m0, s45
	v_lshl_add_u64 v[216:217], s[26:27], 0, v[132:133]
	global_load_lds_dwordx4 v[216:217], off
	s_waitcnt vmcnt(8) lgkmcnt(0)
	s_setprio 1
	s_barrier
	v_mfma_f32_16x16x32_bf16 v[126:129], v[140:143], v[180:183], v[126:129]
	v_mfma_f32_16x16x32_bf16 v[122:125], v[156:159], v[180:183], v[122:125]
	v_mfma_f32_16x16x32_bf16 v[118:121], v[140:143], v[188:191], v[118:121]
	v_mfma_f32_16x16x32_bf16 v[114:117], v[156:159], v[188:191], v[114:117]
	v_mfma_f32_16x16x32_bf16 v[102:105], v[140:143], v[196:199], v[102:105]
	v_mfma_f32_16x16x32_bf16 v[98:101], v[156:159], v[196:199], v[98:101]
	v_mfma_f32_16x16x32_bf16 v[86:89], v[140:143], v[204:207], v[86:89]
	v_mfma_f32_16x16x32_bf16 v[82:85], v[156:159], v[204:207], v[82:85]
	v_mfma_f32_16x16x32_bf16 v[126:129], v[144:147], v[184:187], v[126:129]
	v_mfma_f32_16x16x32_bf16 v[122:125], v[160:163], v[184:187], v[122:125]
	v_mfma_f32_16x16x32_bf16 v[118:121], v[144:147], v[192:195], v[118:121]
	v_mfma_f32_16x16x32_bf16 v[114:117], v[160:163], v[192:195], v[114:117]
	v_mfma_f32_16x16x32_bf16 v[102:105], v[144:147], v[200:203], v[102:105]
	v_mfma_f32_16x16x32_bf16 v[98:101], v[160:163], v[200:203], v[98:101]
	v_mfma_f32_16x16x32_bf16 v[86:89], v[144:147], v[208:211], v[86:89]
	v_mfma_f32_16x16x32_bf16 v[82:85], v[160:163], v[208:211], v[82:85]
	v_mfma_f32_16x16x32_bf16 v[110:113], v[164:167], v[180:183], v[110:113]
	v_mfma_f32_16x16x32_bf16 v[106:109], v[172:175], v[180:183], v[106:109]
	v_mfma_f32_16x16x32_bf16 v[94:97], v[164:167], v[188:191], v[94:97]
	v_mfma_f32_16x16x32_bf16 v[90:93], v[172:175], v[188:191], v[90:93]
	v_mfma_f32_16x16x32_bf16 v[78:81], v[164:167], v[196:199], v[78:81]
	v_mfma_f32_16x16x32_bf16 v[74:77], v[172:175], v[196:199], v[74:77]
	v_mfma_f32_16x16x32_bf16 v[70:73], v[164:167], v[204:207], v[70:73]
	v_mfma_f32_16x16x32_bf16 v[66:69], v[172:175], v[204:207], v[66:69]
	v_mfma_f32_16x16x32_bf16 v[110:113], v[168:171], v[184:187], v[110:113]
	v_mfma_f32_16x16x32_bf16 v[106:109], v[176:179], v[184:187], v[106:109]
	v_mfma_f32_16x16x32_bf16 v[94:97], v[168:171], v[192:195], v[94:97]
	v_mfma_f32_16x16x32_bf16 v[90:93], v[176:179], v[192:195], v[90:93]
	v_mfma_f32_16x16x32_bf16 v[78:81], v[168:171], v[200:203], v[78:81]
	v_mfma_f32_16x16x32_bf16 v[74:77], v[176:179], v[200:203], v[74:77]
	v_mfma_f32_16x16x32_bf16 v[70:73], v[168:171], v[208:211], v[70:73]
	v_mfma_f32_16x16x32_bf16 v[66:69], v[176:179], v[208:211], v[66:69]
	s_setprio 0
	s_barrier
	s_mov_b32 m0, s53
	v_lshl_add_u64 v[148:149], v[148:149], 0, s[70:71]
	ds_read_b128 v[180:183], v139 offset:49152
	ds_read_b128 v[184:187], v139 offset:50176
	ds_read_b128 v[188:191], v139 offset:51200
	ds_read_b128 v[192:195], v139 offset:52224
	ds_read_b128 v[196:199], v139 offset:53248
	ds_read_b128 v[200:203], v139 offset:54272
	ds_read_b128 v[204:207], v139 offset:55296
	ds_read_b128 v[208:211], v139 offset:56320
	global_load_lds_dwordx4 v[148:149], off
	s_mov_b32 m0, s9
	v_lshl_add_u64 v[148:149], v[150:151], 0, s[70:71]
	global_load_lds_dwordx4 v[148:149], off
	s_mov_b32 m0, s96
	v_lshl_add_u64 v[148:149], s[38:39], 0, v[0:1]
	global_load_lds_dwordx4 v[148:149], off
	s_mov_b32 m0, s92
	v_lshl_add_u64 v[148:149], s[38:39], 0, v[130:131]
	global_load_lds_dwordx4 v[148:149], off
	s_mov_b32 m0, s46
	v_lshl_add_u64 v[148:149], v[212:213], 0, s[70:71]
	global_load_lds_dwordx4 v[148:149], off
	s_mov_b32 m0, s47
	v_lshl_add_u64 v[148:149], v[214:215], 0, s[70:71]
	global_load_lds_dwordx4 v[148:149], off
	s_waitcnt vmcnt(8) lgkmcnt(0)
	s_setprio 1
	s_barrier
	v_mfma_f32_16x16x32_bf16 v[62:65], v[140:143], v[180:183], v[62:65]
	v_mfma_f32_16x16x32_bf16 v[58:61], v[156:159], v[180:183], v[58:61]
	v_mfma_f32_16x16x32_bf16 v[54:57], v[140:143], v[188:191], v[54:57]
	v_mfma_f32_16x16x32_bf16 v[50:53], v[156:159], v[188:191], v[50:53]
	v_mfma_f32_16x16x32_bf16 v[38:41], v[140:143], v[196:199], v[38:41]
	v_mfma_f32_16x16x32_bf16 v[34:37], v[156:159], v[196:199], v[34:37]
	v_mfma_f32_16x16x32_bf16 v[22:25], v[140:143], v[204:207], v[22:25]
	v_mfma_f32_16x16x32_bf16 v[18:21], v[156:159], v[204:207], v[18:21]
	v_mfma_f32_16x16x32_bf16 v[62:65], v[144:147], v[184:187], v[62:65]
	v_mfma_f32_16x16x32_bf16 v[58:61], v[160:163], v[184:187], v[58:61]
	v_mfma_f32_16x16x32_bf16 v[54:57], v[144:147], v[192:195], v[54:57]
	v_mfma_f32_16x16x32_bf16 v[50:53], v[160:163], v[192:195], v[50:53]
	v_mfma_f32_16x16x32_bf16 v[38:41], v[144:147], v[200:203], v[38:41]
	v_mfma_f32_16x16x32_bf16 v[34:37], v[160:163], v[200:203], v[34:37]
	v_mfma_f32_16x16x32_bf16 v[22:25], v[144:147], v[208:211], v[22:25]
	v_mfma_f32_16x16x32_bf16 v[18:21], v[160:163], v[208:211], v[18:21]
	v_mfma_f32_16x16x32_bf16 v[46:49], v[164:167], v[180:183], v[46:49]
	v_mfma_f32_16x16x32_bf16 v[42:45], v[172:175], v[180:183], v[42:45]
	v_mfma_f32_16x16x32_bf16 v[30:33], v[164:167], v[188:191], v[30:33]
	v_mfma_f32_16x16x32_bf16 v[26:29], v[172:175], v[188:191], v[26:29]
	v_mfma_f32_16x16x32_bf16 v[14:17], v[164:167], v[196:199], v[14:17]
	v_mfma_f32_16x16x32_bf16 v[10:13], v[172:175], v[196:199], v[10:13]
	v_mfma_f32_16x16x32_bf16 v[6:9], v[164:167], v[204:207], v[6:9]
	v_mfma_f32_16x16x32_bf16 v[2:5], v[172:175], v[204:207], v[2:5]
	v_mfma_f32_16x16x32_bf16 v[46:49], v[168:171], v[184:187], v[46:49]
	v_mfma_f32_16x16x32_bf16 v[42:45], v[176:179], v[184:187], v[42:45]
	v_mfma_f32_16x16x32_bf16 v[30:33], v[168:171], v[192:195], v[30:33]
	v_mfma_f32_16x16x32_bf16 v[26:29], v[176:179], v[192:195], v[26:29]
	v_mfma_f32_16x16x32_bf16 v[14:17], v[168:171], v[200:203], v[14:17]
	v_mfma_f32_16x16x32_bf16 v[10:13], v[176:179], v[200:203], v[10:13]
	v_mfma_f32_16x16x32_bf16 v[6:9], v[168:171], v[208:211], v[6:9]
	v_mfma_f32_16x16x32_bf16 v[2:5], v[176:179], v[208:211], v[2:5]
	s_setprio 0
	s_barrier
	s_movk_i32 s9, 0x100
	s_andn2_b64 vcc, exec, s[4:5]
	s_mov_b64 s[38:39], -1
	s_mov_b64 s[4:5], 0
	s_cbranch_vccz .LBB0_376
	s_and_b64 vcc, exec, s[14:15]
	s_cbranch_vccz .LBB0_379
	s_barrier

.LBB0_393:
	s_ashr_i32 s19, s18, 31
	s_lshl_b64 s[24:25], s[18:19], 16
	s_add_u32 s24, s29, s24
	s_addc_u32 s25, s38, s25
	s_and_b64 s[4:5], s[4:5], exec
	s_cselect_b32 s5, s25, s27
	s_cselect_b32 s4, s24, s26
	s_add_i32 s19, 0, 0x10000
	s_add_i32 s48, 0, 0x14000
	v_add_u32_e32 v14, s19, v137
	v_add_u32_e32 v30, s48, v137
	.p2align 6
	ds_read_b128 v[2:5], v14
	ds_read_b128 v[6:9], v14 offset:1024
	ds_read_b128 v[10:13], v14 offset:2048
	ds_read_b128 v[14:17], v14 offset:3072
	ds_read_b128 v[18:21], v30
	ds_read_b128 v[22:25], v30 offset:1024
	ds_read_b128 v[26:29], v30 offset:2048
	ds_read_b128 v[30:33], v30 offset:3072
	s_add_u32 s26, s36, 0x58080
	s_addc_u32 s27, s37, 0
	v_lshl_add_u64 v[66:67], s[26:27], 0, v[134:135]
	s_add_i32 m0, s40, 0xc000
	ds_read_b128 v[34:37], v139
	ds_read_b128 v[38:41], v139 offset:1024
	ds_read_b128 v[42:45], v139 offset:2048
	ds_read_b128 v[46:49], v139 offset:3072
	ds_read_b128 v[50:53], v139 offset:4096
	ds_read_b128 v[54:57], v139 offset:5120
	ds_read_b128 v[58:61], v139 offset:6144
	ds_read_b128 v[62:65], v139 offset:7168
	global_load_lds_dwordx4 v[66:67], off
	s_add_i32 m0, s40, 0xe000
	v_lshl_add_u64 v[66:67], s[26:27], 0, v[132:133]
	global_load_lds_dwordx4 v[66:67], off
	s_waitcnt vmcnt(8) lgkmcnt(0)
	s_setprio 1
	s_barrier
	v_mfma_f32_16x16x32_bf16 v[66:69], v[2:5], v[34:37], 0
	v_mfma_f32_16x16x32_bf16 v[70:73], v[10:13], v[34:37], 0
	v_mfma_f32_16x16x32_bf16 v[74:77], v[2:5], v[42:45], 0
	v_mfma_f32_16x16x32_bf16 v[78:81], v[10:13], v[42:45], 0
	v_mfma_f32_16x16x32_bf16 v[82:85], v[2:5], v[50:53], 0
	v_mfma_f32_16x16x32_bf16 v[86:89], v[10:13], v[50:53], 0
	v_mfma_f32_16x16x32_bf16 v[90:93], v[2:5], v[58:61], 0
	v_mfma_f32_16x16x32_bf16 v[94:97], v[10:13], v[58:61], 0
	v_mfma_f32_16x16x32_bf16 v[66:69], v[6:9], v[38:41], v[66:69]
	v_mfma_f32_16x16x32_bf16 v[70:73], v[14:17], v[38:41], v[70:73]
	v_mfma_f32_16x16x32_bf16 v[74:77], v[6:9], v[46:49], v[74:77]
	v_mfma_f32_16x16x32_bf16 v[78:81], v[14:17], v[46:49], v[78:81]
	v_mfma_f32_16x16x32_bf16 v[82:85], v[6:9], v[54:57], v[82:85]
	v_mfma_f32_16x16x32_bf16 v[86:89], v[14:17], v[54:57], v[86:89]
	v_mfma_f32_16x16x32_bf16 v[90:93], v[6:9], v[62:65], v[90:93]
	v_mfma_f32_16x16x32_bf16 v[94:97], v[14:17], v[62:65], v[94:97]
	v_mfma_f32_16x16x32_bf16 v[98:101], v[18:21], v[34:37], 0
	v_mfma_f32_16x16x32_bf16 v[34:37], v[26:29], v[34:37], 0
	v_mfma_f32_16x16x32_bf16 v[98:101], v[22:25], v[38:41], v[98:101]
	v_mfma_f32_16x16x32_bf16 v[34:37], v[30:33], v[38:41], v[34:37]
	v_mfma_f32_16x16x32_bf16 v[38:41], v[18:21], v[42:45], 0
	v_mfma_f32_16x16x32_bf16 v[42:45], v[26:29], v[42:45], 0
	v_mfma_f32_16x16x32_bf16 v[102:105], v[30:33], v[46:49], v[42:45]
	v_mfma_f32_16x16x32_bf16 v[42:45], v[18:21], v[50:53], 0
	v_mfma_f32_16x16x32_bf16 v[114:117], v[22:25], v[54:57], v[42:45]
	v_mfma_f32_16x16x32_bf16 v[42:45], v[26:29], v[50:53], 0
	v_mfma_f32_16x16x32_bf16 v[50:53], v[30:33], v[54:57], v[42:45]
	v_mfma_f32_16x16x32_bf16 v[42:45], v[18:21], v[58:61], 0
	v_mfma_f32_16x16x32_bf16 v[54:57], v[22:25], v[62:65], v[42:45]
	v_mfma_f32_16x16x32_bf16 v[42:45], v[26:29], v[58:61], 0
	v_mfma_f32_16x16x32_bf16 v[38:41], v[22:25], v[46:49], v[38:41]
	v_mfma_f32_16x16x32_bf16 v[58:61], v[30:33], v[62:65], v[42:45]
	s_setprio 0
	s_barrier
	s_add_i32 s19, s19, s39
	v_lshl_add_u64 v[148:149], s[4:5], 0, v[0:1]
	s_mov_b32 m0, s19
	s_nop 0
	ds_read_b128 v[42:45], v139 offset:16384
	ds_read_b128 v[46:49], v139 offset:17408
	ds_read_b128 v[62:65], v139 offset:18432
	ds_read_b128 v[106:109], v139 offset:19456
	ds_read_b128 v[110:113], v139 offset:20480
	ds_read_b128 v[118:121], v139 offset:21504
	ds_read_b128 v[122:125], v139 offset:22528
	ds_read_b128 v[126:129], v139 offset:23552
	global_load_lds_dwordx4 v[148:149], off
	s_add_i32 m0, s19, 0x2000
	s_add_u32 s26, s4, 0x8000
	v_lshl_add_u64 v[150:151], s[4:5], 0, v[130:131]
	s_addc_u32 s27, s5, 0
	s_add_i32 s19, s48, s39
	global_load_lds_dwordx4 v[150:151], off
	v_lshl_add_u64 v[140:141], s[26:27], 0, v[0:1]
	s_mov_b32 m0, s19
	v_lshl_add_u64 v[252:253], s[22:23], 0, v[134:135]
	global_load_lds_dwordx4 v[140:141], off
	v_lshl_add_u64 v[140:141], s[26:27], 0, v[130:131]
	s_add_i32 m0, s19, 0x2000
	v_lshl_add_u64 v[242:243], s[22:23], 0, v[132:133]
	global_load_lds_dwordx4 v[140:141], off
	s_mov_b32 m0, s40
	s_nop 0
	global_load_lds_dwordx4 v[252:253], off
	s_mov_b32 m0, s41
	s_nop 0
	global_load_lds_dwordx4 v[242:243], off
	s_waitcnt vmcnt(8) lgkmcnt(0)
	s_setprio 1
	s_barrier
	v_mfma_f32_16x16x32_bf16 v[140:143], v[2:5], v[42:45], 0
	v_mfma_f32_16x16x32_bf16 v[156:159], v[2:5], v[62:65], 0
	v_mfma_f32_16x16x32_bf16 v[164:167], v[2:5], v[110:113], 0
	v_mfma_f32_16x16x32_bf16 v[2:5], v[2:5], v[122:125], 0
	v_mfma_f32_16x16x32_bf16 v[140:143], v[6:9], v[46:49], v[140:143]
	v_mfma_f32_16x16x32_bf16 v[156:159], v[6:9], v[106:109], v[156:159]
	v_mfma_f32_16x16x32_bf16 v[164:167], v[6:9], v[118:121], v[164:167]
	v_mfma_f32_16x16x32_bf16 v[2:5], v[6:9], v[126:129], v[2:5]
	v_mfma_f32_16x16x32_bf16 v[6:9], v[10:13], v[122:125], 0
	v_mfma_f32_16x16x32_bf16 v[144:147], v[10:13], v[42:45], 0
	v_mfma_f32_16x16x32_bf16 v[160:163], v[10:13], v[62:65], 0
	v_mfma_f32_16x16x32_bf16 v[168:171], v[10:13], v[110:113], 0
	v_mfma_f32_16x16x32_bf16 v[6:9], v[14:17], v[126:129], v[6:9]
	v_mfma_f32_16x16x32_bf16 v[144:147], v[14:17], v[46:49], v[144:147]
	v_mfma_f32_16x16x32_bf16 v[160:163], v[14:17], v[106:109], v[160:163]
	v_mfma_f32_16x16x32_bf16 v[168:171], v[14:17], v[118:121], v[168:171]
	v_mfma_f32_16x16x32_bf16 v[10:13], v[18:21], v[42:45], 0
	v_mfma_f32_16x16x32_bf16 v[172:175], v[22:25], v[46:49], v[10:13]
	v_mfma_f32_16x16x32_bf16 v[10:13], v[26:29], v[42:45], 0
	v_mfma_f32_16x16x32_bf16 v[176:179], v[30:33], v[46:49], v[10:13]
	v_mfma_f32_16x16x32_bf16 v[10:13], v[18:21], v[62:65], 0
	v_mfma_f32_16x16x32_bf16 v[180:183], v[22:25], v[106:109], v[10:13]
	v_mfma_f32_16x16x32_bf16 v[10:13], v[26:29], v[62:65], 0
	v_mfma_f32_16x16x32_bf16 v[184:187], v[30:33], v[106:109], v[10:13]
	v_mfma_f32_16x16x32_bf16 v[10:13], v[18:21], v[110:113], 0
	v_mfma_f32_16x16x32_bf16 v[188:191], v[22:25], v[118:121], v[10:13]
	v_mfma_f32_16x16x32_bf16 v[10:13], v[26:29], v[110:113], 0
	v_mfma_f32_16x16x32_bf16 v[192:195], v[30:33], v[118:121], v[10:13]
	v_mfma_f32_16x16x32_bf16 v[10:13], v[18:21], v[122:125], 0
	v_mfma_f32_16x16x32_bf16 v[18:21], v[22:25], v[126:129], v[10:13]
	v_mfma_f32_16x16x32_bf16 v[10:13], v[26:29], v[122:125], 0
	v_mfma_f32_16x16x32_bf16 v[22:25], v[30:33], v[126:129], v[10:13]
	s_setprio 0
	s_barrier
	s_add_i32 s19, 0, 0x18000
	s_nop 3
	v_add_u32_e32 v10, s19, v137
	s_add_i32 s36, 0, 0x1c000
	ds_read_b128 v[118:121], v10
	ds_read_b128 v[196:199], v10 offset:1024
	ds_read_b128 v[200:203], v10 offset:2048
	ds_read_b128 v[204:207], v10 offset:3072
	v_add_u32_e32 v10, s36, v137
	ds_read_b128 v[208:211], v10
	ds_read_b128 v[212:215], v10 offset:1024
	ds_read_b128 v[216:219], v10 offset:2048
	ds_read_b128 v[220:223], v10 offset:3072
	s_add_u32 s26, s22, 0x58000
	s_addc_u32 s27, s23, 0
	s_mov_b32 m0, s42
	v_lshl_add_u64 v[10:11], s[26:27], 0, v[134:135]
	ds_read_b128 v[26:29], v139 offset:32768
	ds_read_b128 v[30:33], v139 offset:33792
	ds_read_b128 v[62:65], v139 offset:34816
	ds_read_b128 v[224:227], v139 offset:35840
	ds_read_b128 v[228:231], v139 offset:36864
	ds_read_b128 v[232:235], v139 offset:37888
	ds_read_b128 v[236:239], v139 offset:38912
	ds_read_b128 v[248:251], v139 offset:39936
	global_load_lds_dwordx4 v[10:11], off
	s_mov_b32 m0, s43
	v_lshl_add_u64 v[10:11], s[26:27], 0, v[132:133]
	global_load_lds_dwordx4 v[10:11], off
	s_waitcnt vmcnt(8) lgkmcnt(0)
	s_setprio 1
	s_barrier
	v_mfma_f32_16x16x32_bf16 v[10:13], v[118:121], v[26:29], v[66:69]
	v_mfma_f32_16x16x32_bf16 v[106:109], v[196:199], v[30:33], v[10:13]
	v_mfma_f32_16x16x32_bf16 v[10:13], v[200:203], v[26:29], v[70:73]
	v_mfma_f32_16x16x32_bf16 v[110:113], v[204:207], v[30:33], v[10:13]
	v_mfma_f32_16x16x32_bf16 v[10:13], v[118:121], v[62:65], v[74:77]
	v_mfma_f32_16x16x32_bf16 v[74:77], v[196:199], v[224:227], v[10:13]
	v_mfma_f32_16x16x32_bf16 v[10:13], v[200:203], v[62:65], v[78:81]
	v_mfma_f32_16x16x32_bf16 v[78:81], v[204:207], v[224:227], v[10:13]
	v_mfma_f32_16x16x32_bf16 v[10:13], v[118:121], v[228:231], v[82:85]
	v_mfma_f32_16x16x32_bf16 v[42:45], v[196:199], v[232:235], v[10:13]
	v_mfma_f32_16x16x32_bf16 v[10:13], v[200:203], v[228:231], v[86:89]
	v_mfma_f32_16x16x32_bf16 v[46:49], v[204:207], v[232:235], v[10:13]
	v_mfma_f32_16x16x32_bf16 v[10:13], v[118:121], v[236:239], v[90:93]
	v_mfma_f32_16x16x32_bf16 v[14:17], v[200:203], v[236:239], v[94:97]
	v_mfma_f32_16x16x32_bf16 v[10:13], v[196:199], v[248:251], v[10:13]
	v_mfma_f32_16x16x32_bf16 v[14:17], v[204:207], v[248:251], v[14:17]
	v_mfma_f32_16x16x32_bf16 v[66:69], v[208:211], v[26:29], v[98:101]
	v_mfma_f32_16x16x32_bf16 v[26:29], v[216:219], v[26:29], v[34:37]
	v_mfma_f32_16x16x32_bf16 v[126:129], v[220:223], v[30:33], v[26:29]
	v_mfma_f32_16x16x32_bf16 v[26:29], v[208:211], v[62:65], v[38:41]
	v_mfma_f32_16x16x32_bf16 v[98:101], v[212:215], v[224:227], v[26:29]
	v_mfma_f32_16x16x32_bf16 v[26:29], v[216:219], v[62:65], v[102:105]
	v_mfma_f32_16x16x32_bf16 v[102:105], v[220:223], v[224:227], v[26:29]
	v_mfma_f32_16x16x32_bf16 v[26:29], v[208:211], v[228:231], v[114:117]
	v_mfma_f32_16x16x32_bf16 v[122:125], v[212:215], v[30:33], v[66:69]
	v_mfma_f32_16x16x32_bf16 v[66:69], v[212:215], v[232:235], v[26:29]
	v_mfma_f32_16x16x32_bf16 v[26:29], v[216:219], v[228:231], v[50:53]
	v_mfma_f32_16x16x32_bf16 v[70:73], v[220:223], v[232:235], v[26:29]
	v_mfma_f32_16x16x32_bf16 v[26:29], v[208:211], v[236:239], v[54:57]
	v_mfma_f32_16x16x32_bf16 v[34:37], v[212:215], v[248:251], v[26:29]
	v_mfma_f32_16x16x32_bf16 v[26:29], v[216:219], v[236:239], v[58:61]
	v_mfma_f32_16x16x32_bf16 v[38:41], v[220:223], v[248:251], v[26:29]
	s_setprio 0
	s_barrier
	s_add_i32 s19, s19, s39
	s_nop 3
	v_lshl_add_u64 v[26:27], v[148:149], 0, s[70:71]
	s_mov_b32 m0, s19
	ds_read_b128 v[50:53], v139 offset:49152
	ds_read_b128 v[54:57], v139 offset:50176
	ds_read_b128 v[86:89], v139 offset:51200
	ds_read_b128 v[224:227], v139 offset:52224
	ds_read_b128 v[228:231], v139 offset:53248
	ds_read_b128 v[232:235], v139 offset:54272
	ds_read_b128 v[236:239], v139 offset:55296
	ds_read_b128 v[248:251], v139 offset:56320
	global_load_lds_dwordx4 v[26:27], off
	s_add_i32 m0, s19, 0x2000
	s_add_u32 s4, s4, 0x8080
	v_lshl_add_u64 v[26:27], v[150:151], 0, s[70:71]
	s_addc_u32 s5, s5, 0
	s_add_i32 s19, s36, s39
	global_load_lds_dwordx4 v[26:27], off
	s_mov_b32 m0, s19
	v_lshl_add_u64 v[26:27], s[4:5], 0, v[0:1]
	global_load_lds_dwordx4 v[26:27], off
	s_add_i32 m0, s19, 0x2000
	v_lshl_add_u64 v[26:27], s[4:5], 0, v[130:131]
	global_load_lds_dwordx4 v[26:27], off
	s_mov_b32 m0, s44
	v_lshl_add_u64 v[26:27], v[252:253], 0, s[70:71]
	global_load_lds_dwordx4 v[26:27], off
	s_mov_b32 m0, s45
	v_lshl_add_u64 v[26:27], v[242:243], 0, s[70:71]
	global_load_lds_dwordx4 v[26:27], off
	s_waitcnt vmcnt(8) lgkmcnt(0)
	s_setprio 1
	s_barrier
	v_mfma_f32_16x16x32_bf16 v[26:29], v[118:121], v[50:53], v[140:143]
	v_mfma_f32_16x16x32_bf16 v[90:93], v[196:199], v[54:57], v[26:29]
	v_mfma_f32_16x16x32_bf16 v[26:29], v[200:203], v[50:53], v[144:147]
	v_mfma_f32_16x16x32_bf16 v[94:97], v[204:207], v[54:57], v[26:29]
	v_mfma_f32_16x16x32_bf16 v[26:29], v[118:121], v[86:89], v[156:159]
	v_mfma_f32_16x16x32_bf16 v[58:61], v[196:199], v[224:227], v[26:29]
	v_mfma_f32_16x16x32_bf16 v[26:29], v[200:203], v[86:89], v[160:163]
	v_mfma_f32_16x16x32_bf16 v[62:65], v[204:207], v[224:227], v[26:29]
	v_mfma_f32_16x16x32_bf16 v[26:29], v[118:121], v[228:231], v[164:167]
	v_mfma_f32_16x16x32_bf16 v[30:33], v[200:203], v[228:231], v[168:171]
	v_mfma_f32_16x16x32_bf16 v[2:5], v[118:121], v[236:239], v[2:5]
	v_mfma_f32_16x16x32_bf16 v[6:9], v[200:203], v[236:239], v[6:9]
	v_mfma_f32_16x16x32_bf16 v[26:29], v[196:199], v[232:235], v[26:29]
	v_mfma_f32_16x16x32_bf16 v[30:33], v[204:207], v[232:235], v[30:33]
	v_mfma_f32_16x16x32_bf16 v[2:5], v[196:199], v[248:251], v[2:5]
	v_mfma_f32_16x16x32_bf16 v[6:9], v[204:207], v[248:251], v[6:9]
	v_mfma_f32_16x16x32_bf16 v[82:85], v[208:211], v[50:53], v[172:175]
	v_mfma_f32_16x16x32_bf16 v[50:53], v[216:219], v[50:53], v[176:179]
	v_mfma_f32_16x16x32_bf16 v[118:121], v[220:223], v[54:57], v[50:53]
	v_mfma_f32_16x16x32_bf16 v[50:53], v[208:211], v[86:89], v[180:183]
	v_mfma_f32_16x16x32_bf16 v[114:117], v[212:215], v[54:57], v[82:85]
	v_mfma_f32_16x16x32_bf16 v[82:85], v[212:215], v[224:227], v[50:53]
	v_mfma_f32_16x16x32_bf16 v[50:53], v[216:219], v[86:89], v[184:187]
	v_mfma_f32_16x16x32_bf16 v[86:89], v[220:223], v[224:227], v[50:53]
	v_mfma_f32_16x16x32_bf16 v[50:53], v[208:211], v[228:231], v[188:191]
	v_mfma_f32_16x16x32_bf16 v[54:57], v[216:219], v[228:231], v[192:195]
	v_mfma_f32_16x16x32_bf16 v[18:21], v[208:211], v[236:239], v[18:21]
	v_mfma_f32_16x16x32_bf16 v[22:25], v[216:219], v[236:239], v[22:25]
	v_mfma_f32_16x16x32_bf16 v[50:53], v[212:215], v[232:235], v[50:53]
	v_mfma_f32_16x16x32_bf16 v[54:57], v[220:223], v[232:235], v[54:57]
	v_mfma_f32_16x16x32_bf16 v[18:21], v[212:215], v[248:251], v[18:21]
	v_mfma_f32_16x16x32_bf16 v[22:25], v[220:223], v[248:251], v[22:25]
	s_setprio 0
	s_barrier
	s_andn2_b64 vcc, exec, s[14:15]
	s_cbranch_vccnz .LBB0_395
	s_barrier

.LBB0_701:
	s_add_i32 s75, s26, 2
	s_add_u32 s9, s60, 0xfffc0080
	s_addc_u32 s27, s61, -1
	s_add_i32 s78, 0, 0x10000
	s_cmp_eq_u32 s19, s26
	s_cselect_b32 s73, s23, s27
	s_cselect_b32 s72, s22, s9
	s_cselect_b32 s27, s25, s29
	s_cselect_b32 s26, s24, s28
	s_add_i32 s9, 0, 0x14000
	s_waitcnt vmcnt(0)
	v_add_u32_e32 v142, s78, v177
	v_add_u32_e32 v148, s9, v177
	ds_read_b128 v[130:133], v142
	ds_read_b128 v[134:137], v142 offset:1024
	ds_read_b128 v[138:141], v142 offset:2048
	ds_read_b128 v[142:145], v142 offset:3072
	ds_read_b128 v[164:167], v148
	ds_read_b128 v[168:171], v148 offset:1024
	ds_read_b128 v[172:175], v148 offset:2048
	ds_read_b128 v[180:183], v148 offset:3072
	v_lshl_add_u64 v[148:149], s[60:61], 0, v[160:161]
	s_add_i32 m0, s37, 0xc000
	ds_read_b128 v[184:187], v179
	ds_read_b128 v[188:191], v179 offset:1024
	ds_read_b128 v[192:195], v179 offset:2048
	ds_read_b128 v[196:199], v179 offset:3072
	ds_read_b128 v[200:203], v179 offset:4096
	ds_read_b128 v[204:207], v179 offset:5120
	ds_read_b128 v[208:211], v179 offset:6144
	ds_read_b128 v[212:215], v179 offset:7168
	global_load_lds_dwordx4 v[148:149], off
	s_add_i32 m0, s37, 0xe000
	v_lshl_add_u64 v[148:149], s[60:61], 0, v[162:163]
	global_load_lds_dwordx4 v[148:149], off
	s_waitcnt vmcnt(8) lgkmcnt(0)
	s_setprio 1
	s_barrier
	v_mfma_f32_16x16x32_bf16 v[126:129], v[130:133], v[184:187], v[126:129]
	v_mfma_f32_16x16x32_bf16 v[122:125], v[138:141], v[184:187], v[122:125]
	v_mfma_f32_16x16x32_bf16 v[110:113], v[130:133], v[192:195], v[110:113]
	v_mfma_f32_16x16x32_bf16 v[106:109], v[138:141], v[192:195], v[106:109]
	v_mfma_f32_16x16x32_bf16 v[94:97], v[130:133], v[200:203], v[94:97]
	v_mfma_f32_16x16x32_bf16 v[90:93], v[138:141], v[200:203], v[90:93]
	v_mfma_f32_16x16x32_bf16 v[78:81], v[130:133], v[208:211], v[78:81]
	v_mfma_f32_16x16x32_bf16 v[74:77], v[138:141], v[208:211], v[74:77]
	v_mfma_f32_16x16x32_bf16 v[126:129], v[134:137], v[188:191], v[126:129]
	v_mfma_f32_16x16x32_bf16 v[122:125], v[142:145], v[188:191], v[122:125]
	v_mfma_f32_16x16x32_bf16 v[110:113], v[134:137], v[196:199], v[110:113]
	v_mfma_f32_16x16x32_bf16 v[106:109], v[142:145], v[196:199], v[106:109]
	v_mfma_f32_16x16x32_bf16 v[94:97], v[134:137], v[204:207], v[94:97]
	v_mfma_f32_16x16x32_bf16 v[90:93], v[142:145], v[204:207], v[90:93]
	v_mfma_f32_16x16x32_bf16 v[78:81], v[134:137], v[212:215], v[78:81]
	v_mfma_f32_16x16x32_bf16 v[74:77], v[142:145], v[212:215], v[74:77]
	v_mfma_f32_16x16x32_bf16 v[118:121], v[164:167], v[184:187], v[118:121]
	v_mfma_f32_16x16x32_bf16 v[114:117], v[172:175], v[184:187], v[114:117]
	v_mfma_f32_16x16x32_bf16 v[102:105], v[164:167], v[192:195], v[102:105]
	v_mfma_f32_16x16x32_bf16 v[98:101], v[172:175], v[192:195], v[98:101]
	v_mfma_f32_16x16x32_bf16 v[86:89], v[164:167], v[200:203], v[86:89]
	v_mfma_f32_16x16x32_bf16 v[82:85], v[172:175], v[200:203], v[82:85]
	v_mfma_f32_16x16x32_bf16 v[70:73], v[164:167], v[208:211], v[70:73]
	v_mfma_f32_16x16x32_bf16 v[66:69], v[172:175], v[208:211], v[66:69]
	v_mfma_f32_16x16x32_bf16 v[118:121], v[168:171], v[188:191], v[118:121]
	v_mfma_f32_16x16x32_bf16 v[114:117], v[180:183], v[188:191], v[114:117]
	v_mfma_f32_16x16x32_bf16 v[102:105], v[168:171], v[196:199], v[102:105]
	v_mfma_f32_16x16x32_bf16 v[98:101], v[180:183], v[196:199], v[98:101]
	v_mfma_f32_16x16x32_bf16 v[86:89], v[168:171], v[204:207], v[86:89]
	v_mfma_f32_16x16x32_bf16 v[82:85], v[180:183], v[204:207], v[82:85]
	v_mfma_f32_16x16x32_bf16 v[70:73], v[168:171], v[212:215], v[70:73]
	v_mfma_f32_16x16x32_bf16 v[66:69], v[180:183], v[212:215], v[66:69]
	s_setprio 0
	s_barrier
	s_add_i32 s78, s78, s41
	v_lshl_add_u64 v[148:149], s[26:27], 0, v[0:1]
	s_mov_b32 m0, s78
	ds_read_b128 v[184:187], v179 offset:16384
	ds_read_b128 v[188:191], v179 offset:17408
	ds_read_b128 v[192:195], v179 offset:18432
	ds_read_b128 v[196:199], v179 offset:19456
	ds_read_b128 v[200:203], v179 offset:20480
	ds_read_b128 v[204:207], v179 offset:21504
	ds_read_b128 v[208:211], v179 offset:22528
	ds_read_b128 v[212:215], v179 offset:23552
	global_load_lds_dwordx4 v[148:149], off
	s_add_i32 m0, s78, 0x2000
	s_add_u32 s78, s26, 0x40000
	v_lshl_add_u64 v[150:151], s[26:27], 0, v[158:159]
	s_addc_u32 s79, s27, 0
	s_add_i32 s9, s9, s41
	global_load_lds_dwordx4 v[150:151], off
	v_lshl_add_u64 v[216:217], s[78:79], 0, v[0:1]
	s_mov_b32 m0, s9
	v_lshl_add_u64 v[218:219], s[72:73], 0, v[156:157]
	global_load_lds_dwordx4 v[216:217], off
	s_add_i32 m0, s9, 0x2000
	v_lshl_add_u64 v[216:217], s[78:79], 0, v[158:159]
	global_load_lds_dwordx4 v[216:217], off
	s_mov_b32 m0, s37
	v_lshl_add_u64 v[216:217], s[72:73], 0, v[146:147]
	global_load_lds_dwordx4 v[216:217], off
	s_mov_b32 m0, s39
	s_nop 0
	global_load_lds_dwordx4 v[218:219], off
	s_waitcnt vmcnt(8) lgkmcnt(0)
	s_setprio 1
	s_barrier
	v_mfma_f32_16x16x32_bf16 v[62:65], v[130:133], v[184:187], v[62:65]
	v_mfma_f32_16x16x32_bf16 v[58:61], v[138:141], v[184:187], v[58:61]
	v_mfma_f32_16x16x32_bf16 v[46:49], v[130:133], v[192:195], v[46:49]
	v_mfma_f32_16x16x32_bf16 v[42:45], v[138:141], v[192:195], v[42:45]
	v_mfma_f32_16x16x32_bf16 v[30:33], v[130:133], v[200:203], v[30:33]
	v_mfma_f32_16x16x32_bf16 v[26:29], v[138:141], v[200:203], v[26:29]
	v_mfma_f32_16x16x32_bf16 v[14:17], v[130:133], v[208:211], v[14:17]
	v_mfma_f32_16x16x32_bf16 v[10:13], v[138:141], v[208:211], v[10:13]
	v_mfma_f32_16x16x32_bf16 v[62:65], v[134:137], v[188:191], v[62:65]
	v_mfma_f32_16x16x32_bf16 v[58:61], v[142:145], v[188:191], v[58:61]
	v_mfma_f32_16x16x32_bf16 v[46:49], v[134:137], v[196:199], v[46:49]
	v_mfma_f32_16x16x32_bf16 v[42:45], v[142:145], v[196:199], v[42:45]
	v_mfma_f32_16x16x32_bf16 v[30:33], v[134:137], v[204:207], v[30:33]
	v_mfma_f32_16x16x32_bf16 v[26:29], v[142:145], v[204:207], v[26:29]
	v_mfma_f32_16x16x32_bf16 v[14:17], v[134:137], v[212:215], v[14:17]
	v_mfma_f32_16x16x32_bf16 v[10:13], v[142:145], v[212:215], v[10:13]
	v_mfma_f32_16x16x32_bf16 v[54:57], v[164:167], v[184:187], v[54:57]
	v_mfma_f32_16x16x32_bf16 v[50:53], v[172:175], v[184:187], v[50:53]
	v_mfma_f32_16x16x32_bf16 v[38:41], v[164:167], v[192:195], v[38:41]
	v_mfma_f32_16x16x32_bf16 v[34:37], v[172:175], v[192:195], v[34:37]
	v_mfma_f32_16x16x32_bf16 v[22:25], v[164:167], v[200:203], v[22:25]
	v_mfma_f32_16x16x32_bf16 v[18:21], v[172:175], v[200:203], v[18:21]
	v_mfma_f32_16x16x32_bf16 v[6:9], v[164:167], v[208:211], v[6:9]
	v_mfma_f32_16x16x32_bf16 v[2:5], v[172:175], v[208:211], v[2:5]
	v_mfma_f32_16x16x32_bf16 v[54:57], v[168:171], v[188:191], v[54:57]
	v_mfma_f32_16x16x32_bf16 v[50:53], v[180:183], v[188:191], v[50:53]
	v_mfma_f32_16x16x32_bf16 v[38:41], v[168:171], v[196:199], v[38:41]
	v_mfma_f32_16x16x32_bf16 v[34:37], v[180:183], v[196:199], v[34:37]
	v_mfma_f32_16x16x32_bf16 v[22:25], v[168:171], v[204:207], v[22:25]
	v_mfma_f32_16x16x32_bf16 v[18:21], v[180:183], v[204:207], v[18:21]
	v_mfma_f32_16x16x32_bf16 v[6:9], v[168:171], v[212:215], v[6:9]
	v_mfma_f32_16x16x32_bf16 v[2:5], v[180:183], v[212:215], v[2:5]
	s_setprio 0
	s_barrier
	s_add_i32 s9, 0, 0x18000
	s_add_i32 s78, 0, 0x1c000
	v_add_u32_e32 v142, s9, v177
	v_add_u32_e32 v180, s78, v177
	ds_read_b128 v[130:133], v142
	ds_read_b128 v[134:137], v142 offset:1024
	ds_read_b128 v[138:141], v142 offset:2048
	ds_read_b128 v[142:145], v142 offset:3072
	ds_read_b128 v[164:167], v180
	ds_read_b128 v[168:171], v180 offset:1024
	ds_read_b128 v[172:175], v180 offset:2048
	ds_read_b128 v[180:183], v180 offset:3072
	s_add_u32 s72, s72, 0x40000
	s_addc_u32 s73, s73, 0
	s_mov_b32 m0, s44
	v_lshl_add_u64 v[220:221], s[72:73], 0, v[146:147]
	ds_read_b128 v[184:187], v179 offset:32768
	ds_read_b128 v[188:191], v179 offset:33792
	ds_read_b128 v[192:195], v179 offset:34816
	ds_read_b128 v[196:199], v179 offset:35840
	ds_read_b128 v[200:203], v179 offset:36864
	ds_read_b128 v[204:207], v179 offset:37888
	ds_read_b128 v[208:211], v179 offset:38912
	ds_read_b128 v[212:215], v179 offset:39936
	global_load_lds_dwordx4 v[220:221], off
	s_mov_b32 m0, s45
	v_lshl_add_u64 v[220:221], s[72:73], 0, v[156:157]
	global_load_lds_dwordx4 v[220:221], off
	s_waitcnt vmcnt(8) lgkmcnt(0)
	s_setprio 1
	s_barrier
	v_mfma_f32_16x16x32_bf16 v[126:129], v[130:133], v[184:187], v[126:129]
	v_mfma_f32_16x16x32_bf16 v[122:125], v[138:141], v[184:187], v[122:125]
	v_mfma_f32_16x16x32_bf16 v[110:113], v[130:133], v[192:195], v[110:113]
	v_mfma_f32_16x16x32_bf16 v[106:109], v[138:141], v[192:195], v[106:109]
	v_mfma_f32_16x16x32_bf16 v[94:97], v[130:133], v[200:203], v[94:97]
	v_mfma_f32_16x16x32_bf16 v[90:93], v[138:141], v[200:203], v[90:93]
	v_mfma_f32_16x16x32_bf16 v[78:81], v[130:133], v[208:211], v[78:81]
	v_mfma_f32_16x16x32_bf16 v[74:77], v[138:141], v[208:211], v[74:77]
	v_mfma_f32_16x16x32_bf16 v[126:129], v[134:137], v[188:191], v[126:129]
	v_mfma_f32_16x16x32_bf16 v[122:125], v[142:145], v[188:191], v[122:125]
	v_mfma_f32_16x16x32_bf16 v[110:113], v[134:137], v[196:199], v[110:113]
	v_mfma_f32_16x16x32_bf16 v[106:109], v[142:145], v[196:199], v[106:109]
	v_mfma_f32_16x16x32_bf16 v[94:97], v[134:137], v[204:207], v[94:97]
	v_mfma_f32_16x16x32_bf16 v[90:93], v[142:145], v[204:207], v[90:93]
	v_mfma_f32_16x16x32_bf16 v[78:81], v[134:137], v[212:215], v[78:81]
	v_mfma_f32_16x16x32_bf16 v[74:77], v[142:145], v[212:215], v[74:77]
	v_mfma_f32_16x16x32_bf16 v[118:121], v[164:167], v[184:187], v[118:121]
	v_mfma_f32_16x16x32_bf16 v[114:117], v[172:175], v[184:187], v[114:117]
	v_mfma_f32_16x16x32_bf16 v[102:105], v[164:167], v[192:195], v[102:105]
	v_mfma_f32_16x16x32_bf16 v[98:101], v[172:175], v[192:195], v[98:101]
	v_mfma_f32_16x16x32_bf16 v[86:89], v[164:167], v[200:203], v[86:89]
	v_mfma_f32_16x16x32_bf16 v[82:85], v[172:175], v[200:203], v[82:85]
	v_mfma_f32_16x16x32_bf16 v[70:73], v[164:167], v[208:211], v[70:73]
	v_mfma_f32_16x16x32_bf16 v[66:69], v[172:175], v[208:211], v[66:69]
	v_mfma_f32_16x16x32_bf16 v[118:121], v[168:171], v[188:191], v[118:121]
	v_mfma_f32_16x16x32_bf16 v[114:117], v[180:183], v[188:191], v[114:117]
	v_mfma_f32_16x16x32_bf16 v[102:105], v[168:171], v[196:199], v[102:105]
	v_mfma_f32_16x16x32_bf16 v[98:101], v[180:183], v[196:199], v[98:101]
	v_mfma_f32_16x16x32_bf16 v[86:89], v[168:171], v[204:207], v[86:89]
	v_mfma_f32_16x16x32_bf16 v[82:85], v[180:183], v[204:207], v[82:85]
	v_mfma_f32_16x16x32_bf16 v[70:73], v[168:171], v[212:215], v[70:73]
	v_mfma_f32_16x16x32_bf16 v[66:69], v[180:183], v[212:215], v[66:69]
	s_setprio 0
	s_barrier
	s_add_i32 s9, s9, s41
	v_lshl_add_u64 v[148:149], v[148:149], 0, s[70:71]
	s_mov_b32 m0, s9
	ds_read_b128 v[184:187], v179 offset:49152
	ds_read_b128 v[188:191], v179 offset:50176
	ds_read_b128 v[192:195], v179 offset:51200
	ds_read_b128 v[196:199], v179 offset:52224
	ds_read_b128 v[200:203], v179 offset:53248
	ds_read_b128 v[204:207], v179 offset:54272
	ds_read_b128 v[208:211], v179 offset:55296
	ds_read_b128 v[212:215], v179 offset:56320
	global_load_lds_dwordx4 v[148:149], off
	s_add_i32 m0, s9, 0x2000
	s_add_u32 s26, s26, 0x40080
	v_lshl_add_u64 v[148:149], v[150:151], 0, s[70:71]
	s_addc_u32 s27, s27, 0
	s_add_i32 s9, s78, s41
	global_load_lds_dwordx4 v[148:149], off
	s_mov_b32 m0, s9
	v_lshl_add_u64 v[148:149], s[26:27], 0, v[0:1]
	global_load_lds_dwordx4 v[148:149], off
	s_add_i32 m0, s9, 0x2000
	v_lshl_add_u64 v[148:149], s[26:27], 0, v[158:159]
	global_load_lds_dwordx4 v[148:149], off
	s_mov_b32 m0, s50
	v_lshl_add_u64 v[148:149], v[216:217], 0, s[70:71]
	global_load_lds_dwordx4 v[148:149], off
	s_mov_b32 m0, s51
	v_lshl_add_u64 v[148:149], v[218:219], 0, s[70:71]
	global_load_lds_dwordx4 v[148:149], off
	s_waitcnt vmcnt(8) lgkmcnt(0)
	s_setprio 1
	s_barrier
	v_mfma_f32_16x16x32_bf16 v[62:65], v[130:133], v[184:187], v[62:65]
	v_mfma_f32_16x16x32_bf16 v[58:61], v[138:141], v[184:187], v[58:61]
	v_mfma_f32_16x16x32_bf16 v[46:49], v[130:133], v[192:195], v[46:49]
	v_mfma_f32_16x16x32_bf16 v[42:45], v[138:141], v[192:195], v[42:45]
	v_mfma_f32_16x16x32_bf16 v[30:33], v[130:133], v[200:203], v[30:33]
	v_mfma_f32_16x16x32_bf16 v[26:29], v[138:141], v[200:203], v[26:29]
	v_mfma_f32_16x16x32_bf16 v[14:17], v[130:133], v[208:211], v[14:17]
	v_mfma_f32_16x16x32_bf16 v[10:13], v[138:141], v[208:211], v[10:13]
	v_mfma_f32_16x16x32_bf16 v[62:65], v[134:137], v[188:191], v[62:65]
	v_mfma_f32_16x16x32_bf16 v[58:61], v[142:145], v[188:191], v[58:61]
	v_mfma_f32_16x16x32_bf16 v[46:49], v[134:137], v[196:199], v[46:49]
	v_mfma_f32_16x16x32_bf16 v[42:45], v[142:145], v[196:199], v[42:45]
	v_mfma_f32_16x16x32_bf16 v[30:33], v[134:137], v[204:207], v[30:33]
	v_mfma_f32_16x16x32_bf16 v[26:29], v[142:145], v[204:207], v[26:29]
	v_mfma_f32_16x16x32_bf16 v[14:17], v[134:137], v[212:215], v[14:17]
	v_mfma_f32_16x16x32_bf16 v[10:13], v[142:145], v[212:215], v[10:13]
	v_mfma_f32_16x16x32_bf16 v[54:57], v[164:167], v[184:187], v[54:57]
	v_mfma_f32_16x16x32_bf16 v[50:53], v[172:175], v[184:187], v[50:53]
	v_mfma_f32_16x16x32_bf16 v[38:41], v[164:167], v[192:195], v[38:41]
	v_mfma_f32_16x16x32_bf16 v[34:37], v[172:175], v[192:195], v[34:37]
	v_mfma_f32_16x16x32_bf16 v[22:25], v[164:167], v[200:203], v[22:25]
	v_mfma_f32_16x16x32_bf16 v[18:21], v[172:175], v[200:203], v[18:21]
	v_mfma_f32_16x16x32_bf16 v[6:9], v[164:167], v[208:211], v[6:9]
	v_mfma_f32_16x16x32_bf16 v[2:5], v[172:175], v[208:211], v[2:5]
	v_mfma_f32_16x16x32_bf16 v[54:57], v[168:171], v[188:191], v[54:57]
	v_mfma_f32_16x16x32_bf16 v[50:53], v[180:183], v[188:191], v[50:53]
	v_mfma_f32_16x16x32_bf16 v[38:41], v[168:171], v[196:199], v[38:41]
	v_mfma_f32_16x16x32_bf16 v[34:37], v[180:183], v[196:199], v[34:37]
	v_mfma_f32_16x16x32_bf16 v[22:25], v[168:171], v[204:207], v[22:25]
	v_mfma_f32_16x16x32_bf16 v[18:21], v[180:183], v[204:207], v[18:21]
	v_mfma_f32_16x16x32_bf16 v[6:9], v[168:171], v[212:215], v[6:9]
	v_mfma_f32_16x16x32_bf16 v[2:5], v[180:183], v[212:215], v[2:5]
	s_setprio 0
	s_barrier
	s_add_u32 s60, s60, 0x100
	s_addc_u32 s61, s61, 0
	s_add_u32 s28, s28, 0x100
	s_addc_u32 s29, s29, 0
	s_cmp_ge_u32 s75, s17
	s_mov_b32 s26, s75
	s_cbranch_scc0 .LBB0_701
	s_and_b64 vcc, exec, s[14:15]
	s_cbranch_vccz .LBB0_704

.LBB0_846:
	s_add_u32 s9, s96, 0xfffc0080
	s_addc_u32 s38, s97, -1
	s_add_i32 s78, 0, 0x10000
	s_cmp_eq_u32 s75, 12
	s_cselect_b32 vcc_hi, s25, s38
	s_cselect_b32 vcc_lo, s28, s9
	v_add_u32_e32 v148, s78, v145
	s_cselect_b32 s39, s23, s61
	s_cselect_b32 s38, s29, s53
	s_add_i32 s9, 0, 0x14000
	ds_read_b128 v[140:143], v148
	ds_read_b128 v[156:159], v148 offset:1024
	ds_read_b128 v[160:163], v148 offset:2048
	ds_read_b128 v[164:167], v148 offset:3072
	v_add_u32_e32 v148, s9, v145
	ds_read_b128 v[168:171], v148
	ds_read_b128 v[172:175], v148 offset:1024
	ds_read_b128 v[176:179], v148 offset:2048
	ds_read_b128 v[180:183], v148 offset:3072
	v_lshl_add_u64 v[148:149], s[96:97], 0, v[136:137]
	s_add_i32 m0, s46, 0xc000
	ds_read_b128 v[184:187], v147
	ds_read_b128 v[188:191], v147 offset:1024
	ds_read_b128 v[192:195], v147 offset:2048
	ds_read_b128 v[196:199], v147 offset:3072
	ds_read_b128 v[200:203], v147 offset:4096
	ds_read_b128 v[204:207], v147 offset:5120
	ds_read_b128 v[208:211], v147 offset:6144
	ds_read_b128 v[212:215], v147 offset:7168
	global_load_lds_dwordx4 v[148:149], off
	s_add_i32 m0, s46, 0xe000
	v_lshl_add_u64 v[148:149], s[96:97], 0, v[138:139]
	global_load_lds_dwordx4 v[148:149], off
	s_waitcnt vmcnt(8) lgkmcnt(0)
	s_setprio 1
	s_barrier
	v_mfma_f32_16x16x32_bf16 v[126:129], v[140:143], v[184:187], v[126:129]
	v_mfma_f32_16x16x32_bf16 v[118:121], v[160:163], v[184:187], v[118:121]
	v_mfma_f32_16x16x32_bf16 v[110:113], v[140:143], v[192:195], v[110:113]
	v_mfma_f32_16x16x32_bf16 v[102:105], v[160:163], v[192:195], v[102:105]
	v_mfma_f32_16x16x32_bf16 v[94:97], v[140:143], v[200:203], v[94:97]
	v_mfma_f32_16x16x32_bf16 v[86:89], v[160:163], v[200:203], v[86:89]
	v_mfma_f32_16x16x32_bf16 v[78:81], v[140:143], v[208:211], v[78:81]
	v_mfma_f32_16x16x32_bf16 v[70:73], v[160:163], v[208:211], v[70:73]
	v_mfma_f32_16x16x32_bf16 v[126:129], v[156:159], v[188:191], v[126:129]
	v_mfma_f32_16x16x32_bf16 v[118:121], v[164:167], v[188:191], v[118:121]
	v_mfma_f32_16x16x32_bf16 v[110:113], v[156:159], v[196:199], v[110:113]
	v_mfma_f32_16x16x32_bf16 v[102:105], v[164:167], v[196:199], v[102:105]
	v_mfma_f32_16x16x32_bf16 v[94:97], v[156:159], v[204:207], v[94:97]
	v_mfma_f32_16x16x32_bf16 v[86:89], v[164:167], v[204:207], v[86:89]
	v_mfma_f32_16x16x32_bf16 v[78:81], v[156:159], v[212:215], v[78:81]
	v_mfma_f32_16x16x32_bf16 v[70:73], v[164:167], v[212:215], v[70:73]
	v_mfma_f32_16x16x32_bf16 v[122:125], v[168:171], v[184:187], v[122:125]
	v_mfma_f32_16x16x32_bf16 v[114:117], v[176:179], v[184:187], v[114:117]
	v_mfma_f32_16x16x32_bf16 v[106:109], v[168:171], v[192:195], v[106:109]
	v_mfma_f32_16x16x32_bf16 v[98:101], v[176:179], v[192:195], v[98:101]
	v_mfma_f32_16x16x32_bf16 v[90:93], v[168:171], v[200:203], v[90:93]
	v_mfma_f32_16x16x32_bf16 v[82:85], v[176:179], v[200:203], v[82:85]
	v_mfma_f32_16x16x32_bf16 v[74:77], v[168:171], v[208:211], v[74:77]
	v_mfma_f32_16x16x32_bf16 v[66:69], v[176:179], v[208:211], v[66:69]
	v_mfma_f32_16x16x32_bf16 v[122:125], v[172:175], v[188:191], v[122:125]
	v_mfma_f32_16x16x32_bf16 v[114:117], v[180:183], v[188:191], v[114:117]
	v_mfma_f32_16x16x32_bf16 v[106:109], v[172:175], v[196:199], v[106:109]
	v_mfma_f32_16x16x32_bf16 v[98:101], v[180:183], v[196:199], v[98:101]
	v_mfma_f32_16x16x32_bf16 v[90:93], v[172:175], v[204:207], v[90:93]
	v_mfma_f32_16x16x32_bf16 v[82:85], v[180:183], v[204:207], v[82:85]
	v_mfma_f32_16x16x32_bf16 v[74:77], v[172:175], v[212:215], v[74:77]
	v_mfma_f32_16x16x32_bf16 v[66:69], v[180:183], v[212:215], v[66:69]
	s_setprio 0
	s_barrier
	s_add_i32 s78, s78, s45
	v_lshl_add_u64 v[148:149], s[38:39], 0, v[0:1]
	s_mov_b32 m0, s78
	ds_read_b128 v[184:187], v147 offset:16384
	ds_read_b128 v[188:191], v147 offset:17408
	ds_read_b128 v[192:195], v147 offset:18432
	ds_read_b128 v[196:199], v147 offset:19456
	ds_read_b128 v[200:203], v147 offset:20480
	ds_read_b128 v[204:207], v147 offset:21504
	ds_read_b128 v[208:211], v147 offset:22528
	ds_read_b128 v[212:215], v147 offset:23552
	global_load_lds_dwordx4 v[148:149], off
	s_add_i32 m0, s78, 0x2000
	s_add_u32 s78, s38, 0x40000
	v_lshl_add_u64 v[150:151], s[38:39], 0, v[134:135]
	s_addc_u32 s79, s39, 0
	s_add_i32 s9, s9, s45
	global_load_lds_dwordx4 v[150:151], off
	v_lshl_add_u64 v[216:217], s[78:79], 0, v[0:1]
	s_mov_b32 m0, s9
	v_lshl_add_u64 v[218:219], vcc, 0, v[132:133]
	global_load_lds_dwordx4 v[216:217], off
	s_add_i32 m0, s9, 0x2000
	v_lshl_add_u64 v[216:217], s[78:79], 0, v[134:135]
	global_load_lds_dwordx4 v[216:217], off
	s_mov_b32 m0, s46
	v_lshl_add_u64 v[216:217], vcc, 0, v[130:131]
	global_load_lds_dwordx4 v[216:217], off
	s_mov_b32 m0, s47
	s_nop 0
	global_load_lds_dwordx4 v[218:219], off
	s_waitcnt vmcnt(8) lgkmcnt(0)
	s_setprio 1
	s_barrier
	v_mfma_f32_16x16x32_bf16 v[62:65], v[140:143], v[184:187], v[62:65]
	v_mfma_f32_16x16x32_bf16 v[54:57], v[160:163], v[184:187], v[54:57]
	v_mfma_f32_16x16x32_bf16 v[46:49], v[140:143], v[192:195], v[46:49]
	v_mfma_f32_16x16x32_bf16 v[38:41], v[160:163], v[192:195], v[38:41]
	v_mfma_f32_16x16x32_bf16 v[30:33], v[140:143], v[200:203], v[30:33]
	v_mfma_f32_16x16x32_bf16 v[22:25], v[160:163], v[200:203], v[22:25]
	v_mfma_f32_16x16x32_bf16 v[14:17], v[140:143], v[208:211], v[14:17]
	v_mfma_f32_16x16x32_bf16 v[6:9], v[160:163], v[208:211], v[6:9]
	v_mfma_f32_16x16x32_bf16 v[62:65], v[156:159], v[188:191], v[62:65]
	v_mfma_f32_16x16x32_bf16 v[54:57], v[164:167], v[188:191], v[54:57]
	v_mfma_f32_16x16x32_bf16 v[46:49], v[156:159], v[196:199], v[46:49]
	v_mfma_f32_16x16x32_bf16 v[38:41], v[164:167], v[196:199], v[38:41]
	v_mfma_f32_16x16x32_bf16 v[30:33], v[156:159], v[204:207], v[30:33]
	v_mfma_f32_16x16x32_bf16 v[22:25], v[164:167], v[204:207], v[22:25]
	v_mfma_f32_16x16x32_bf16 v[14:17], v[156:159], v[212:215], v[14:17]
	v_mfma_f32_16x16x32_bf16 v[6:9], v[164:167], v[212:215], v[6:9]
	v_mfma_f32_16x16x32_bf16 v[58:61], v[168:171], v[184:187], v[58:61]
	v_mfma_f32_16x16x32_bf16 v[50:53], v[176:179], v[184:187], v[50:53]
	v_mfma_f32_16x16x32_bf16 v[42:45], v[168:171], v[192:195], v[42:45]
	v_mfma_f32_16x16x32_bf16 v[34:37], v[176:179], v[192:195], v[34:37]
	v_mfma_f32_16x16x32_bf16 v[26:29], v[168:171], v[200:203], v[26:29]
	v_mfma_f32_16x16x32_bf16 v[18:21], v[176:179], v[200:203], v[18:21]
	v_mfma_f32_16x16x32_bf16 v[10:13], v[168:171], v[208:211], v[10:13]
	v_mfma_f32_16x16x32_bf16 v[2:5], v[176:179], v[208:211], v[2:5]
	v_mfma_f32_16x16x32_bf16 v[58:61], v[172:175], v[188:191], v[58:61]
	v_mfma_f32_16x16x32_bf16 v[50:53], v[180:183], v[188:191], v[50:53]
	v_mfma_f32_16x16x32_bf16 v[42:45], v[172:175], v[196:199], v[42:45]
	v_mfma_f32_16x16x32_bf16 v[34:37], v[180:183], v[196:199], v[34:37]
	v_mfma_f32_16x16x32_bf16 v[26:29], v[172:175], v[204:207], v[26:29]
	v_mfma_f32_16x16x32_bf16 v[18:21], v[180:183], v[204:207], v[18:21]
	v_mfma_f32_16x16x32_bf16 v[10:13], v[172:175], v[212:215], v[10:13]
	v_mfma_f32_16x16x32_bf16 v[2:5], v[180:183], v[212:215], v[2:5]
	s_setprio 0
	s_barrier
	s_add_i32 s9, 0, 0x18000
	s_add_i32 s83, 0, 0x1c000
	v_add_u32_e32 v164, s9, v145
	v_add_u32_e32 v180, s83, v145
	ds_read_b128 v[140:143], v164
	ds_read_b128 v[156:159], v164 offset:1024
	ds_read_b128 v[160:163], v164 offset:2048
	ds_read_b128 v[164:167], v164 offset:3072
	ds_read_b128 v[168:171], v180
	ds_read_b128 v[172:175], v180 offset:1024
	ds_read_b128 v[176:179], v180 offset:2048
	ds_read_b128 v[180:183], v180 offset:3072
	s_add_u32 s78, vcc_lo, 0x40000
	s_addc_u32 s79, vcc_hi, 0
	s_mov_b32 m0, s48
	v_lshl_add_u64 v[220:221], s[78:79], 0, v[130:131]
	ds_read_b128 v[184:187], v147 offset:32768
	ds_read_b128 v[188:191], v147 offset:33792
	ds_read_b128 v[192:195], v147 offset:34816
	ds_read_b128 v[196:199], v147 offset:35840
	ds_read_b128 v[200:203], v147 offset:36864
	ds_read_b128 v[204:207], v147 offset:37888
	ds_read_b128 v[208:211], v147 offset:38912
	ds_read_b128 v[212:215], v147 offset:39936
	global_load_lds_dwordx4 v[220:221], off
	s_mov_b32 m0, s49
	v_lshl_add_u64 v[220:221], s[78:79], 0, v[132:133]
	global_load_lds_dwordx4 v[220:221], off
	s_waitcnt vmcnt(8) lgkmcnt(0)
	s_setprio 1
	s_barrier
	v_mfma_f32_16x16x32_bf16 v[126:129], v[140:143], v[184:187], v[126:129]
	v_mfma_f32_16x16x32_bf16 v[118:121], v[160:163], v[184:187], v[118:121]
	v_mfma_f32_16x16x32_bf16 v[110:113], v[140:143], v[192:195], v[110:113]
	v_mfma_f32_16x16x32_bf16 v[102:105], v[160:163], v[192:195], v[102:105]
	v_mfma_f32_16x16x32_bf16 v[94:97], v[140:143], v[200:203], v[94:97]
	v_mfma_f32_16x16x32_bf16 v[86:89], v[160:163], v[200:203], v[86:89]
	v_mfma_f32_16x16x32_bf16 v[78:81], v[140:143], v[208:211], v[78:81]
	v_mfma_f32_16x16x32_bf16 v[70:73], v[160:163], v[208:211], v[70:73]
	v_mfma_f32_16x16x32_bf16 v[126:129], v[156:159], v[188:191], v[126:129]
	v_mfma_f32_16x16x32_bf16 v[118:121], v[164:167], v[188:191], v[118:121]
	v_mfma_f32_16x16x32_bf16 v[110:113], v[156:159], v[196:199], v[110:113]
	v_mfma_f32_16x16x32_bf16 v[102:105], v[164:167], v[196:199], v[102:105]
	v_mfma_f32_16x16x32_bf16 v[94:97], v[156:159], v[204:207], v[94:97]
	v_mfma_f32_16x16x32_bf16 v[86:89], v[164:167], v[204:207], v[86:89]
	v_mfma_f32_16x16x32_bf16 v[78:81], v[156:159], v[212:215], v[78:81]
	v_mfma_f32_16x16x32_bf16 v[70:73], v[164:167], v[212:215], v[70:73]
	v_mfma_f32_16x16x32_bf16 v[122:125], v[168:171], v[184:187], v[122:125]
	v_mfma_f32_16x16x32_bf16 v[114:117], v[176:179], v[184:187], v[114:117]
	v_mfma_f32_16x16x32_bf16 v[106:109], v[168:171], v[192:195], v[106:109]
	v_mfma_f32_16x16x32_bf16 v[98:101], v[176:179], v[192:195], v[98:101]
	v_mfma_f32_16x16x32_bf16 v[90:93], v[168:171], v[200:203], v[90:93]
	v_mfma_f32_16x16x32_bf16 v[82:85], v[176:179], v[200:203], v[82:85]
	v_mfma_f32_16x16x32_bf16 v[74:77], v[168:171], v[208:211], v[74:77]
	v_mfma_f32_16x16x32_bf16 v[66:69], v[176:179], v[208:211], v[66:69]
	v_mfma_f32_16x16x32_bf16 v[122:125], v[172:175], v[188:191], v[122:125]
	v_mfma_f32_16x16x32_bf16 v[114:117], v[180:183], v[188:191], v[114:117]
	v_mfma_f32_16x16x32_bf16 v[106:109], v[172:175], v[196:199], v[106:109]
	v_mfma_f32_16x16x32_bf16 v[98:101], v[180:183], v[196:199], v[98:101]
	v_mfma_f32_16x16x32_bf16 v[90:93], v[172:175], v[204:207], v[90:93]
	v_mfma_f32_16x16x32_bf16 v[82:85], v[180:183], v[204:207], v[82:85]
	v_mfma_f32_16x16x32_bf16 v[74:77], v[172:175], v[212:215], v[74:77]
	v_mfma_f32_16x16x32_bf16 v[66:69], v[180:183], v[212:215], v[66:69]
	s_setprio 0
	s_barrier
	s_add_i32 s9, s9, s45
	v_lshl_add_u64 v[148:149], v[148:149], 0, s[70:71]
	s_mov_b32 m0, s9
	ds_read_b128 v[184:187], v147 offset:49152
	ds_read_b128 v[188:191], v147 offset:50176
	ds_read_b128 v[192:195], v147 offset:51200
	ds_read_b128 v[196:199], v147 offset:52224
	ds_read_b128 v[200:203], v147 offset:53248
	ds_read_b128 v[204:207], v147 offset:54272
	ds_read_b128 v[208:211], v147 offset:55296
	ds_read_b128 v[212:215], v147 offset:56320
	global_load_lds_dwordx4 v[148:149], off
	s_add_i32 m0, s9, 0x2000
	s_add_u32 s38, s38, 0x40080
	v_lshl_add_u64 v[148:149], v[150:151], 0, s[70:71]
	s_addc_u32 s39, s39, 0
	s_add_i32 s9, s83, s45
	global_load_lds_dwordx4 v[148:149], off
	s_mov_b32 m0, s9
	v_lshl_add_u64 v[148:149], s[38:39], 0, v[0:1]
	global_load_lds_dwordx4 v[148:149], off
	s_add_i32 m0, s9, 0x2000
	v_lshl_add_u64 v[148:149], s[38:39], 0, v[134:135]
	global_load_lds_dwordx4 v[148:149], off
	s_mov_b32 m0, s50
	v_lshl_add_u64 v[148:149], v[216:217], 0, s[70:71]
	global_load_lds_dwordx4 v[148:149], off
	s_mov_b32 m0, s51
	v_lshl_add_u64 v[148:149], v[218:219], 0, s[70:71]
	global_load_lds_dwordx4 v[148:149], off
	s_waitcnt vmcnt(8) lgkmcnt(0)
	s_setprio 1
	s_barrier
	v_mfma_f32_16x16x32_bf16 v[62:65], v[140:143], v[184:187], v[62:65]
	v_mfma_f32_16x16x32_bf16 v[54:57], v[160:163], v[184:187], v[54:57]
	v_mfma_f32_16x16x32_bf16 v[46:49], v[140:143], v[192:195], v[46:49]
	v_mfma_f32_16x16x32_bf16 v[38:41], v[160:163], v[192:195], v[38:41]
	v_mfma_f32_16x16x32_bf16 v[30:33], v[140:143], v[200:203], v[30:33]
	v_mfma_f32_16x16x32_bf16 v[22:25], v[160:163], v[200:203], v[22:25]
	v_mfma_f32_16x16x32_bf16 v[14:17], v[140:143], v[208:211], v[14:17]
	v_mfma_f32_16x16x32_bf16 v[6:9], v[160:163], v[208:211], v[6:9]
	v_mfma_f32_16x16x32_bf16 v[62:65], v[156:159], v[188:191], v[62:65]
	v_mfma_f32_16x16x32_bf16 v[54:57], v[164:167], v[188:191], v[54:57]
	v_mfma_f32_16x16x32_bf16 v[46:49], v[156:159], v[196:199], v[46:49]
	v_mfma_f32_16x16x32_bf16 v[38:41], v[164:167], v[196:199], v[38:41]
	v_mfma_f32_16x16x32_bf16 v[30:33], v[156:159], v[204:207], v[30:33]
	v_mfma_f32_16x16x32_bf16 v[22:25], v[164:167], v[204:207], v[22:25]
	v_mfma_f32_16x16x32_bf16 v[14:17], v[156:159], v[212:215], v[14:17]
	v_mfma_f32_16x16x32_bf16 v[6:9], v[164:167], v[212:215], v[6:9]
	v_mfma_f32_16x16x32_bf16 v[58:61], v[168:171], v[184:187], v[58:61]
	v_mfma_f32_16x16x32_bf16 v[50:53], v[176:179], v[184:187], v[50:53]
	v_mfma_f32_16x16x32_bf16 v[42:45], v[168:171], v[192:195], v[42:45]
	v_mfma_f32_16x16x32_bf16 v[34:37], v[176:179], v[192:195], v[34:37]
	v_mfma_f32_16x16x32_bf16 v[26:29], v[168:171], v[200:203], v[26:29]
	v_mfma_f32_16x16x32_bf16 v[18:21], v[176:179], v[200:203], v[18:21]
	v_mfma_f32_16x16x32_bf16 v[10:13], v[168:171], v[208:211], v[10:13]
	v_mfma_f32_16x16x32_bf16 v[2:5], v[176:179], v[208:211], v[2:5]
	v_mfma_f32_16x16x32_bf16 v[58:61], v[172:175], v[188:191], v[58:61]
	v_mfma_f32_16x16x32_bf16 v[50:53], v[180:183], v[188:191], v[50:53]
	v_mfma_f32_16x16x32_bf16 v[42:45], v[172:175], v[196:199], v[42:45]
	v_mfma_f32_16x16x32_bf16 v[34:37], v[180:183], v[196:199], v[34:37]
	v_mfma_f32_16x16x32_bf16 v[26:29], v[172:175], v[204:207], v[26:29]
	v_mfma_f32_16x16x32_bf16 v[18:21], v[180:183], v[204:207], v[18:21]
	v_mfma_f32_16x16x32_bf16 v[10:13], v[172:175], v[212:215], v[10:13]
	v_mfma_f32_16x16x32_bf16 v[2:5], v[180:183], v[212:215], v[2:5]
	s_setprio 0
	s_barrier
	s_add_i32 s75, s75, 2
	s_add_u32 s96, s96, 0x100
	s_addc_u32 s97, s97, 0
	s_add_u32 s53, s53, 0x100
	s_addc_u32 s61, s61, 0
	s_cmp_gt_u32 s75, 13
	s_cbranch_scc0 .LBB0_846
	s_and_b64 vcc, exec, s[14:15]
	s_cbranch_vccz .LBB0_849
	s_barrier

.LBB0_950:
	s_add_i32 s9, s26, 2
	s_add_u32 s60, s38, 0x100
	s_addc_u32 s61, s39, 0
	s_add_i32 s78, 0, 0x10000
	s_cmp_eq_u32 s29, s26
	s_cselect_b32 s73, s25, s61
	s_cselect_b32 s72, s24, s60
	s_cselect_b32 s27, s37, vcc_hi
	s_cselect_b32 s26, s36, vcc_lo
	s_add_i32 s79, 0, 0x14000
	v_add_u32_e32 v156, s78, v177
	v_add_u32_e32 v172, s79, v177
	ds_read_b128 v[140:143], v156
	ds_read_b128 v[144:147], v156 offset:1024
	ds_read_b128 v[148:151], v156 offset:2048
	ds_read_b128 v[156:159], v156 offset:3072
	ds_read_b128 v[160:163], v172
	ds_read_b128 v[164:167], v172 offset:1024
	ds_read_b128 v[168:171], v172 offset:2048
	ds_read_b128 v[172:175], v172 offset:3072
	v_lshl_add_u64 v[212:213], s[38:39], 0, v[136:137]
	s_add_i32 m0, s50, 0xc000
	ds_read_b128 v[180:183], v179
	ds_read_b128 v[184:187], v179 offset:1024
	ds_read_b128 v[188:191], v179 offset:2048
	ds_read_b128 v[192:195], v179 offset:3072
	ds_read_b128 v[196:199], v179 offset:4096
	ds_read_b128 v[200:203], v179 offset:5120
	ds_read_b128 v[204:207], v179 offset:6144
	ds_read_b128 v[208:211], v179 offset:7168
	global_load_lds_dwordx4 v[212:213], off
	s_add_i32 m0, s50, 0xe000
	v_lshl_add_u64 v[212:213], s[38:39], 0, v[138:139]
	global_load_lds_dwordx4 v[212:213], off
	s_waitcnt vmcnt(8) lgkmcnt(0)
	s_setprio 1
	s_barrier
	v_mfma_f32_16x16x32_bf16 v[126:129], v[140:143], v[180:183], v[126:129]
	v_mfma_f32_16x16x32_bf16 v[122:125], v[148:151], v[180:183], v[122:125]
	v_mfma_f32_16x16x32_bf16 v[110:113], v[140:143], v[188:191], v[110:113]
	v_mfma_f32_16x16x32_bf16 v[106:109], v[148:151], v[188:191], v[106:109]
	v_mfma_f32_16x16x32_bf16 v[94:97], v[140:143], v[196:199], v[94:97]
	v_mfma_f32_16x16x32_bf16 v[90:93], v[148:151], v[196:199], v[90:93]
	v_mfma_f32_16x16x32_bf16 v[78:81], v[140:143], v[204:207], v[78:81]
	v_mfma_f32_16x16x32_bf16 v[74:77], v[148:151], v[204:207], v[74:77]
	v_mfma_f32_16x16x32_bf16 v[126:129], v[144:147], v[184:187], v[126:129]
	v_mfma_f32_16x16x32_bf16 v[122:125], v[156:159], v[184:187], v[122:125]
	v_mfma_f32_16x16x32_bf16 v[110:113], v[144:147], v[192:195], v[110:113]
	v_mfma_f32_16x16x32_bf16 v[106:109], v[156:159], v[192:195], v[106:109]
	v_mfma_f32_16x16x32_bf16 v[94:97], v[144:147], v[200:203], v[94:97]
	v_mfma_f32_16x16x32_bf16 v[90:93], v[156:159], v[200:203], v[90:93]
	v_mfma_f32_16x16x32_bf16 v[78:81], v[144:147], v[208:211], v[78:81]
	v_mfma_f32_16x16x32_bf16 v[74:77], v[156:159], v[208:211], v[74:77]
	v_mfma_f32_16x16x32_bf16 v[118:121], v[160:163], v[180:183], v[118:121]
	v_mfma_f32_16x16x32_bf16 v[114:117], v[168:171], v[180:183], v[114:117]
	v_mfma_f32_16x16x32_bf16 v[102:105], v[160:163], v[188:191], v[102:105]
	v_mfma_f32_16x16x32_bf16 v[98:101], v[168:171], v[188:191], v[98:101]
	v_mfma_f32_16x16x32_bf16 v[86:89], v[160:163], v[196:199], v[86:89]
	v_mfma_f32_16x16x32_bf16 v[82:85], v[168:171], v[196:199], v[82:85]
	v_mfma_f32_16x16x32_bf16 v[70:73], v[160:163], v[204:207], v[70:73]
	v_mfma_f32_16x16x32_bf16 v[66:69], v[168:171], v[204:207], v[66:69]
	v_mfma_f32_16x16x32_bf16 v[118:121], v[164:167], v[184:187], v[118:121]
	v_mfma_f32_16x16x32_bf16 v[114:117], v[172:175], v[184:187], v[114:117]
	v_mfma_f32_16x16x32_bf16 v[102:105], v[164:167], v[192:195], v[102:105]
	v_mfma_f32_16x16x32_bf16 v[98:101], v[172:175], v[192:195], v[98:101]
	v_mfma_f32_16x16x32_bf16 v[86:89], v[164:167], v[200:203], v[86:89]
	v_mfma_f32_16x16x32_bf16 v[82:85], v[172:175], v[200:203], v[82:85]
	v_mfma_f32_16x16x32_bf16 v[70:73], v[164:167], v[208:211], v[70:73]
	v_mfma_f32_16x16x32_bf16 v[66:69], v[172:175], v[208:211], v[66:69]
	s_setprio 0
	s_barrier
	s_add_i32 s38, s78, s49
	v_lshl_add_u64 v[212:213], s[26:27], 0, v[0:1]
	s_mov_b32 m0, s38
	ds_read_b128 v[180:183], v179 offset:16384
	ds_read_b128 v[184:187], v179 offset:17408
	ds_read_b128 v[188:191], v179 offset:18432
	ds_read_b128 v[192:195], v179 offset:19456
	ds_read_b128 v[196:199], v179 offset:20480
	ds_read_b128 v[200:203], v179 offset:21504
	ds_read_b128 v[204:207], v179 offset:22528
	ds_read_b128 v[208:211], v179 offset:23552
	global_load_lds_dwordx4 v[212:213], off
	s_add_i32 m0, s38, 0x2000
	s_add_u32 s38, s26, 0xb0000
	v_lshl_add_u64 v[214:215], s[26:27], 0, v[134:135]
	s_addc_u32 s39, s27, 0
	s_add_i32 s78, s79, s49
	global_load_lds_dwordx4 v[214:215], off
	v_lshl_add_u64 v[216:217], s[38:39], 0, v[0:1]
	s_mov_b32 m0, s78
	v_lshl_add_u64 v[218:219], s[72:73], 0, v[132:133]
	global_load_lds_dwordx4 v[216:217], off
	s_add_i32 m0, s78, 0x2000
	v_lshl_add_u64 v[216:217], s[38:39], 0, v[134:135]
	global_load_lds_dwordx4 v[216:217], off
	s_mov_b32 m0, s50
	v_lshl_add_u64 v[216:217], s[72:73], 0, v[130:131]
	global_load_lds_dwordx4 v[216:217], off
	s_mov_b32 m0, s51
	s_nop 0
	global_load_lds_dwordx4 v[218:219], off
	s_waitcnt vmcnt(8) lgkmcnt(0)
	s_setprio 1
	s_barrier
	v_mfma_f32_16x16x32_bf16 v[62:65], v[140:143], v[180:183], v[62:65]
	v_mfma_f32_16x16x32_bf16 v[58:61], v[148:151], v[180:183], v[58:61]
	v_mfma_f32_16x16x32_bf16 v[46:49], v[140:143], v[188:191], v[46:49]
	v_mfma_f32_16x16x32_bf16 v[42:45], v[148:151], v[188:191], v[42:45]
	v_mfma_f32_16x16x32_bf16 v[30:33], v[140:143], v[196:199], v[30:33]
	v_mfma_f32_16x16x32_bf16 v[26:29], v[148:151], v[196:199], v[26:29]
	v_mfma_f32_16x16x32_bf16 v[14:17], v[140:143], v[204:207], v[14:17]
	v_mfma_f32_16x16x32_bf16 v[10:13], v[148:151], v[204:207], v[10:13]
	v_mfma_f32_16x16x32_bf16 v[62:65], v[144:147], v[184:187], v[62:65]
	v_mfma_f32_16x16x32_bf16 v[58:61], v[156:159], v[184:187], v[58:61]
	v_mfma_f32_16x16x32_bf16 v[46:49], v[144:147], v[192:195], v[46:49]
	v_mfma_f32_16x16x32_bf16 v[42:45], v[156:159], v[192:195], v[42:45]
	v_mfma_f32_16x16x32_bf16 v[30:33], v[144:147], v[200:203], v[30:33]
	v_mfma_f32_16x16x32_bf16 v[26:29], v[156:159], v[200:203], v[26:29]
	v_mfma_f32_16x16x32_bf16 v[14:17], v[144:147], v[208:211], v[14:17]
	v_mfma_f32_16x16x32_bf16 v[10:13], v[156:159], v[208:211], v[10:13]
	v_mfma_f32_16x16x32_bf16 v[54:57], v[160:163], v[180:183], v[54:57]
	v_mfma_f32_16x16x32_bf16 v[50:53], v[168:171], v[180:183], v[50:53]
	v_mfma_f32_16x16x32_bf16 v[38:41], v[160:163], v[188:191], v[38:41]
	v_mfma_f32_16x16x32_bf16 v[34:37], v[168:171], v[188:191], v[34:37]
	v_mfma_f32_16x16x32_bf16 v[22:25], v[160:163], v[196:199], v[22:25]
	v_mfma_f32_16x16x32_bf16 v[18:21], v[168:171], v[196:199], v[18:21]
	v_mfma_f32_16x16x32_bf16 v[6:9], v[160:163], v[204:207], v[6:9]
	v_mfma_f32_16x16x32_bf16 v[2:5], v[168:171], v[204:207], v[2:5]
	v_mfma_f32_16x16x32_bf16 v[54:57], v[164:167], v[184:187], v[54:57]
	v_mfma_f32_16x16x32_bf16 v[50:53], v[172:175], v[184:187], v[50:53]
	v_mfma_f32_16x16x32_bf16 v[38:41], v[164:167], v[192:195], v[38:41]
	v_mfma_f32_16x16x32_bf16 v[34:37], v[172:175], v[192:195], v[34:37]
	v_mfma_f32_16x16x32_bf16 v[22:25], v[164:167], v[200:203], v[22:25]
	v_mfma_f32_16x16x32_bf16 v[18:21], v[172:175], v[200:203], v[18:21]
	v_mfma_f32_16x16x32_bf16 v[6:9], v[164:167], v[208:211], v[6:9]
	v_mfma_f32_16x16x32_bf16 v[2:5], v[172:175], v[208:211], v[2:5]
	s_setprio 0
	s_barrier
	s_add_i32 s78, 0, 0x18000
	s_add_i32 s79, 0, 0x1c000
	v_add_u32_e32 v156, s78, v177
	v_add_u32_e32 v172, s79, v177
	ds_read_b128 v[140:143], v156
	ds_read_b128 v[144:147], v156 offset:1024
	ds_read_b128 v[148:151], v156 offset:2048
	ds_read_b128 v[156:159], v156 offset:3072
	ds_read_b128 v[160:163], v172
	ds_read_b128 v[164:167], v172 offset:1024
	ds_read_b128 v[168:171], v172 offset:2048
	ds_read_b128 v[172:175], v172 offset:3072
	s_add_u32 s38, s72, 0xb0000
	s_addc_u32 s39, s73, 0
	s_mov_b32 m0, s52
	v_lshl_add_u64 v[220:221], s[38:39], 0, v[130:131]
	ds_read_b128 v[180:183], v179 offset:32768
	ds_read_b128 v[184:187], v179 offset:33792
	ds_read_b128 v[188:191], v179 offset:34816
	ds_read_b128 v[192:195], v179 offset:35840
	ds_read_b128 v[196:199], v179 offset:36864
	ds_read_b128 v[200:203], v179 offset:37888
	ds_read_b128 v[204:207], v179 offset:38912
	ds_read_b128 v[208:211], v179 offset:39936
	global_load_lds_dwordx4 v[220:221], off
	s_mov_b32 m0, s53
	v_lshl_add_u64 v[220:221], s[38:39], 0, v[132:133]
	global_load_lds_dwordx4 v[220:221], off
	s_waitcnt vmcnt(8) lgkmcnt(0)
	s_setprio 1
	s_barrier
	v_mfma_f32_16x16x32_bf16 v[126:129], v[140:143], v[180:183], v[126:129]
	v_mfma_f32_16x16x32_bf16 v[122:125], v[148:151], v[180:183], v[122:125]
	v_mfma_f32_16x16x32_bf16 v[110:113], v[140:143], v[188:191], v[110:113]
	v_mfma_f32_16x16x32_bf16 v[106:109], v[148:151], v[188:191], v[106:109]
	v_mfma_f32_16x16x32_bf16 v[94:97], v[140:143], v[196:199], v[94:97]
	v_mfma_f32_16x16x32_bf16 v[90:93], v[148:151], v[196:199], v[90:93]
	v_mfma_f32_16x16x32_bf16 v[78:81], v[140:143], v[204:207], v[78:81]
	v_mfma_f32_16x16x32_bf16 v[74:77], v[148:151], v[204:207], v[74:77]
	v_mfma_f32_16x16x32_bf16 v[126:129], v[144:147], v[184:187], v[126:129]
	v_mfma_f32_16x16x32_bf16 v[122:125], v[156:159], v[184:187], v[122:125]
	v_mfma_f32_16x16x32_bf16 v[110:113], v[144:147], v[192:195], v[110:113]
	v_mfma_f32_16x16x32_bf16 v[106:109], v[156:159], v[192:195], v[106:109]
	v_mfma_f32_16x16x32_bf16 v[94:97], v[144:147], v[200:203], v[94:97]
	v_mfma_f32_16x16x32_bf16 v[90:93], v[156:159], v[200:203], v[90:93]
	v_mfma_f32_16x16x32_bf16 v[78:81], v[144:147], v[208:211], v[78:81]
	v_mfma_f32_16x16x32_bf16 v[74:77], v[156:159], v[208:211], v[74:77]
	v_mfma_f32_16x16x32_bf16 v[118:121], v[160:163], v[180:183], v[118:121]
	v_mfma_f32_16x16x32_bf16 v[114:117], v[168:171], v[180:183], v[114:117]
	v_mfma_f32_16x16x32_bf16 v[102:105], v[160:163], v[188:191], v[102:105]
	v_mfma_f32_16x16x32_bf16 v[98:101], v[168:171], v[188:191], v[98:101]
	v_mfma_f32_16x16x32_bf16 v[86:89], v[160:163], v[196:199], v[86:89]
	v_mfma_f32_16x16x32_bf16 v[82:85], v[168:171], v[196:199], v[82:85]
	v_mfma_f32_16x16x32_bf16 v[70:73], v[160:163], v[204:207], v[70:73]
	v_mfma_f32_16x16x32_bf16 v[66:69], v[168:171], v[204:207], v[66:69]
	v_mfma_f32_16x16x32_bf16 v[118:121], v[164:167], v[184:187], v[118:121]
	v_mfma_f32_16x16x32_bf16 v[114:117], v[172:175], v[184:187], v[114:117]
	v_mfma_f32_16x16x32_bf16 v[102:105], v[164:167], v[192:195], v[102:105]
	v_mfma_f32_16x16x32_bf16 v[98:101], v[172:175], v[192:195], v[98:101]
	v_mfma_f32_16x16x32_bf16 v[86:89], v[164:167], v[200:203], v[86:89]
	v_mfma_f32_16x16x32_bf16 v[82:85], v[172:175], v[200:203], v[82:85]
	v_mfma_f32_16x16x32_bf16 v[70:73], v[164:167], v[208:211], v[70:73]
	v_mfma_f32_16x16x32_bf16 v[66:69], v[172:175], v[208:211], v[66:69]
	s_setprio 0
	s_barrier
	s_add_i32 s38, s78, s49
	v_lshl_add_u64 v[212:213], v[212:213], 0, s[70:71]
	s_mov_b32 m0, s38
	ds_read_b128 v[180:183], v179 offset:49152
	ds_read_b128 v[184:187], v179 offset:50176
	ds_read_b128 v[188:191], v179 offset:51200
	ds_read_b128 v[192:195], v179 offset:52224
	ds_read_b128 v[196:199], v179 offset:53248
	ds_read_b128 v[200:203], v179 offset:54272
	ds_read_b128 v[204:207], v179 offset:55296
	ds_read_b128 v[208:211], v179 offset:56320
	global_load_lds_dwordx4 v[212:213], off
	s_add_i32 m0, s38, 0x2000
	s_add_u32 s26, s26, 0xb0080
	v_lshl_add_u64 v[212:213], v[214:215], 0, s[70:71]
	s_addc_u32 s27, s27, 0
	s_add_i32 s38, s79, s49
	global_load_lds_dwordx4 v[212:213], off
	s_mov_b32 m0, s38
	v_lshl_add_u64 v[212:213], s[26:27], 0, v[0:1]
	global_load_lds_dwordx4 v[212:213], off
	s_add_i32 m0, s38, 0x2000
	v_lshl_add_u64 v[212:213], s[26:27], 0, v[134:135]
	global_load_lds_dwordx4 v[212:213], off
	s_mov_b32 m0, s74
	v_lshl_add_u64 v[212:213], v[216:217], 0, s[70:71]
	global_load_lds_dwordx4 v[212:213], off
	s_mov_b32 m0, s75
	v_lshl_add_u64 v[212:213], v[218:219], 0, s[70:71]
	global_load_lds_dwordx4 v[212:213], off
	s_waitcnt vmcnt(8) lgkmcnt(0)
	s_setprio 1
	s_barrier
	v_mfma_f32_16x16x32_bf16 v[62:65], v[140:143], v[180:183], v[62:65]
	v_mfma_f32_16x16x32_bf16 v[58:61], v[148:151], v[180:183], v[58:61]
	v_mfma_f32_16x16x32_bf16 v[46:49], v[140:143], v[188:191], v[46:49]
	v_mfma_f32_16x16x32_bf16 v[42:45], v[148:151], v[188:191], v[42:45]
	v_mfma_f32_16x16x32_bf16 v[30:33], v[140:143], v[196:199], v[30:33]
	v_mfma_f32_16x16x32_bf16 v[26:29], v[148:151], v[196:199], v[26:29]
	v_mfma_f32_16x16x32_bf16 v[14:17], v[140:143], v[204:207], v[14:17]
	v_mfma_f32_16x16x32_bf16 v[10:13], v[148:151], v[204:207], v[10:13]
	v_mfma_f32_16x16x32_bf16 v[62:65], v[144:147], v[184:187], v[62:65]
	v_mfma_f32_16x16x32_bf16 v[58:61], v[156:159], v[184:187], v[58:61]
	v_mfma_f32_16x16x32_bf16 v[46:49], v[144:147], v[192:195], v[46:49]
	v_mfma_f32_16x16x32_bf16 v[42:45], v[156:159], v[192:195], v[42:45]
	v_mfma_f32_16x16x32_bf16 v[30:33], v[144:147], v[200:203], v[30:33]
	v_mfma_f32_16x16x32_bf16 v[26:29], v[156:159], v[200:203], v[26:29]
	v_mfma_f32_16x16x32_bf16 v[14:17], v[144:147], v[208:211], v[14:17]
	v_mfma_f32_16x16x32_bf16 v[10:13], v[156:159], v[208:211], v[10:13]
	v_mfma_f32_16x16x32_bf16 v[54:57], v[160:163], v[180:183], v[54:57]
	v_mfma_f32_16x16x32_bf16 v[50:53], v[168:171], v[180:183], v[50:53]
	v_mfma_f32_16x16x32_bf16 v[38:41], v[160:163], v[188:191], v[38:41]
	v_mfma_f32_16x16x32_bf16 v[34:37], v[168:171], v[188:191], v[34:37]
	v_mfma_f32_16x16x32_bf16 v[22:25], v[160:163], v[196:199], v[22:25]
	v_mfma_f32_16x16x32_bf16 v[18:21], v[168:171], v[196:199], v[18:21]
	v_mfma_f32_16x16x32_bf16 v[6:9], v[160:163], v[204:207], v[6:9]
	v_mfma_f32_16x16x32_bf16 v[2:5], v[168:171], v[204:207], v[2:5]
	v_mfma_f32_16x16x32_bf16 v[54:57], v[164:167], v[184:187], v[54:57]
	v_mfma_f32_16x16x32_bf16 v[50:53], v[172:175], v[184:187], v[50:53]
	v_mfma_f32_16x16x32_bf16 v[38:41], v[164:167], v[192:195], v[38:41]
	v_mfma_f32_16x16x32_bf16 v[34:37], v[172:175], v[192:195], v[34:37]
	v_mfma_f32_16x16x32_bf16 v[22:25], v[164:167], v[200:203], v[22:25]
	v_mfma_f32_16x16x32_bf16 v[18:21], v[172:175], v[200:203], v[18:21]
	v_mfma_f32_16x16x32_bf16 v[6:9], v[164:167], v[208:211], v[6:9]
	v_mfma_f32_16x16x32_bf16 v[2:5], v[172:175], v[208:211], v[2:5]
	s_setprio 0
	s_barrier
	s_add_u32 vcc_lo, vcc_lo, 0x100
	s_addc_u32 vcc_hi, vcc_hi, 0
	s_cmp_ge_u32 s9, s28
	s_mov_b64 s[38:39], s[60:61]
	s_mov_b32 s26, s9
	s_cbranch_scc0 .LBB0_950
	s_and_b64 vcc, exec, s[22:23]
	s_cbranch_vccz .LBB0_953

.LBB0_1000:
	s_add_i32 s9, s26, 2
	s_add_u32 s60, s38, 0x100
	s_addc_u32 s61, s39, 0
	s_add_i32 s78, 0, 0x10000
	s_cmp_eq_u32 s29, s26
	s_cselect_b32 s73, s25, s61
	s_cselect_b32 s72, s24, s60
	v_add_u32_e32 v148, s78, v251
	s_cselect_b32 s27, s37, vcc_hi
	s_cselect_b32 s26, s36, vcc_lo
	s_add_i32 s79, 0, 0x14000
	ds_read_b128 v[140:143], v148
	ds_read_b128 v[144:147], v148 offset:1024
	ds_read_b128 v[156:159], v148 offset:2048
	ds_read_b128 v[160:163], v148 offset:3072
	v_add_u32_e32 v148, s79, v251
	ds_read_b128 v[164:167], v148
	ds_read_b128 v[168:171], v148 offset:1024
	ds_read_b128 v[172:175], v148 offset:2048
	ds_read_b128 v[176:179], v148 offset:3072
	v_lshl_add_u64 v[148:149], s[38:39], 0, v[136:137]
	s_add_i32 m0, s50, 0xc000
	ds_read_b128 v[180:183], v253
	ds_read_b128 v[184:187], v253 offset:1024
	ds_read_b128 v[188:191], v253 offset:2048
	ds_read_b128 v[192:195], v253 offset:3072
	ds_read_b128 v[196:199], v253 offset:4096
	ds_read_b128 v[200:203], v253 offset:5120
	ds_read_b128 v[204:207], v253 offset:6144
	ds_read_b128 v[208:211], v253 offset:7168
	global_load_lds_dwordx4 v[148:149], off
	s_add_i32 m0, s50, 0xe000
	v_lshl_add_u64 v[148:149], s[38:39], 0, v[138:139]
	global_load_lds_dwordx4 v[148:149], off
	s_waitcnt vmcnt(8) lgkmcnt(0)
	s_setprio 1
	s_barrier
	v_mfma_f32_16x16x32_bf16 v[126:129], v[140:143], v[180:183], v[126:129]
	v_mfma_f32_16x16x32_bf16 v[122:125], v[156:159], v[180:183], v[122:125]
	v_mfma_f32_16x16x32_bf16 v[110:113], v[140:143], v[188:191], v[110:113]
	v_mfma_f32_16x16x32_bf16 v[106:109], v[156:159], v[188:191], v[106:109]
	v_mfma_f32_16x16x32_bf16 v[94:97], v[140:143], v[196:199], v[94:97]
	v_mfma_f32_16x16x32_bf16 v[90:93], v[156:159], v[196:199], v[90:93]
	v_mfma_f32_16x16x32_bf16 v[78:81], v[140:143], v[204:207], v[78:81]
	v_mfma_f32_16x16x32_bf16 v[74:77], v[156:159], v[204:207], v[74:77]
	v_mfma_f32_16x16x32_bf16 v[126:129], v[144:147], v[184:187], v[126:129]
	v_mfma_f32_16x16x32_bf16 v[122:125], v[160:163], v[184:187], v[122:125]
	v_mfma_f32_16x16x32_bf16 v[110:113], v[144:147], v[192:195], v[110:113]
	v_mfma_f32_16x16x32_bf16 v[106:109], v[160:163], v[192:195], v[106:109]
	v_mfma_f32_16x16x32_bf16 v[94:97], v[144:147], v[200:203], v[94:97]
	v_mfma_f32_16x16x32_bf16 v[90:93], v[160:163], v[200:203], v[90:93]
	v_mfma_f32_16x16x32_bf16 v[78:81], v[144:147], v[208:211], v[78:81]
	v_mfma_f32_16x16x32_bf16 v[74:77], v[160:163], v[208:211], v[74:77]
	v_mfma_f32_16x16x32_bf16 v[118:121], v[164:167], v[180:183], v[118:121]
	v_mfma_f32_16x16x32_bf16 v[114:117], v[172:175], v[180:183], v[114:117]
	v_mfma_f32_16x16x32_bf16 v[102:105], v[164:167], v[188:191], v[102:105]
	v_mfma_f32_16x16x32_bf16 v[98:101], v[172:175], v[188:191], v[98:101]
	v_mfma_f32_16x16x32_bf16 v[86:89], v[164:167], v[196:199], v[86:89]
	v_mfma_f32_16x16x32_bf16 v[82:85], v[172:175], v[196:199], v[82:85]
	v_mfma_f32_16x16x32_bf16 v[70:73], v[164:167], v[204:207], v[70:73]
	v_mfma_f32_16x16x32_bf16 v[66:69], v[172:175], v[204:207], v[66:69]
	v_mfma_f32_16x16x32_bf16 v[118:121], v[168:171], v[184:187], v[118:121]
	v_mfma_f32_16x16x32_bf16 v[114:117], v[176:179], v[184:187], v[114:117]
	v_mfma_f32_16x16x32_bf16 v[102:105], v[168:171], v[192:195], v[102:105]
	v_mfma_f32_16x16x32_bf16 v[98:101], v[176:179], v[192:195], v[98:101]
	v_mfma_f32_16x16x32_bf16 v[86:89], v[168:171], v[200:203], v[86:89]
	v_mfma_f32_16x16x32_bf16 v[82:85], v[176:179], v[200:203], v[82:85]
	v_mfma_f32_16x16x32_bf16 v[70:73], v[168:171], v[208:211], v[70:73]
	v_mfma_f32_16x16x32_bf16 v[66:69], v[176:179], v[208:211], v[66:69]
	s_setprio 0
	s_barrier
	s_add_i32 s38, s78, s49
	v_lshl_add_u64 v[148:149], s[26:27], 0, v[0:1]
	s_mov_b32 m0, s38
	ds_read_b128 v[180:183], v253 offset:16384
	ds_read_b128 v[184:187], v253 offset:17408
	ds_read_b128 v[188:191], v253 offset:18432
	ds_read_b128 v[192:195], v253 offset:19456
	ds_read_b128 v[196:199], v253 offset:20480
	ds_read_b128 v[200:203], v253 offset:21504
	ds_read_b128 v[204:207], v253 offset:22528
	ds_read_b128 v[208:211], v253 offset:23552
	global_load_lds_dwordx4 v[148:149], off
	s_add_i32 m0, s38, 0x2000
	s_add_u32 s38, s26, 0xb0000
	v_lshl_add_u64 v[150:151], s[26:27], 0, v[134:135]
	s_addc_u32 s39, s27, 0
	s_add_i32 s78, s79, s49
	global_load_lds_dwordx4 v[150:151], off
	v_lshl_add_u64 v[212:213], s[38:39], 0, v[0:1]
	s_mov_b32 m0, s78
	v_lshl_add_u64 v[214:215], s[72:73], 0, v[132:133]
	global_load_lds_dwordx4 v[212:213], off
	s_add_i32 m0, s78, 0x2000
	v_lshl_add_u64 v[212:213], s[38:39], 0, v[134:135]
	global_load_lds_dwordx4 v[212:213], off
	s_mov_b32 m0, s50
	v_lshl_add_u64 v[212:213], s[72:73], 0, v[130:131]
	global_load_lds_dwordx4 v[212:213], off
	s_mov_b32 m0, s51
	s_nop 0
	global_load_lds_dwordx4 v[214:215], off
	s_waitcnt vmcnt(8) lgkmcnt(0)
	s_setprio 1
	s_barrier
	v_mfma_f32_16x16x32_bf16 v[62:65], v[140:143], v[180:183], v[62:65]
	v_mfma_f32_16x16x32_bf16 v[58:61], v[156:159], v[180:183], v[58:61]
	v_mfma_f32_16x16x32_bf16 v[46:49], v[140:143], v[188:191], v[46:49]
	v_mfma_f32_16x16x32_bf16 v[42:45], v[156:159], v[188:191], v[42:45]
	v_mfma_f32_16x16x32_bf16 v[30:33], v[140:143], v[196:199], v[30:33]
	v_mfma_f32_16x16x32_bf16 v[26:29], v[156:159], v[196:199], v[26:29]
	v_mfma_f32_16x16x32_bf16 v[14:17], v[140:143], v[204:207], v[14:17]
	v_mfma_f32_16x16x32_bf16 v[10:13], v[156:159], v[204:207], v[10:13]
	v_mfma_f32_16x16x32_bf16 v[62:65], v[144:147], v[184:187], v[62:65]
	v_mfma_f32_16x16x32_bf16 v[58:61], v[160:163], v[184:187], v[58:61]
	v_mfma_f32_16x16x32_bf16 v[46:49], v[144:147], v[192:195], v[46:49]
	v_mfma_f32_16x16x32_bf16 v[42:45], v[160:163], v[192:195], v[42:45]
	v_mfma_f32_16x16x32_bf16 v[30:33], v[144:147], v[200:203], v[30:33]
	v_mfma_f32_16x16x32_bf16 v[26:29], v[160:163], v[200:203], v[26:29]
	v_mfma_f32_16x16x32_bf16 v[14:17], v[144:147], v[208:211], v[14:17]
	v_mfma_f32_16x16x32_bf16 v[10:13], v[160:163], v[208:211], v[10:13]
	v_mfma_f32_16x16x32_bf16 v[54:57], v[164:167], v[180:183], v[54:57]
	v_mfma_f32_16x16x32_bf16 v[50:53], v[172:175], v[180:183], v[50:53]
	v_mfma_f32_16x16x32_bf16 v[38:41], v[164:167], v[188:191], v[38:41]
	v_mfma_f32_16x16x32_bf16 v[34:37], v[172:175], v[188:191], v[34:37]
	v_mfma_f32_16x16x32_bf16 v[22:25], v[164:167], v[196:199], v[22:25]
	v_mfma_f32_16x16x32_bf16 v[18:21], v[172:175], v[196:199], v[18:21]
	v_mfma_f32_16x16x32_bf16 v[6:9], v[164:167], v[204:207], v[6:9]
	v_mfma_f32_16x16x32_bf16 v[2:5], v[172:175], v[204:207], v[2:5]
	v_mfma_f32_16x16x32_bf16 v[54:57], v[168:171], v[184:187], v[54:57]
	v_mfma_f32_16x16x32_bf16 v[50:53], v[176:179], v[184:187], v[50:53]
	v_mfma_f32_16x16x32_bf16 v[38:41], v[168:171], v[192:195], v[38:41]
	v_mfma_f32_16x16x32_bf16 v[34:37], v[176:179], v[192:195], v[34:37]
	v_mfma_f32_16x16x32_bf16 v[22:25], v[168:171], v[200:203], v[22:25]
	v_mfma_f32_16x16x32_bf16 v[18:21], v[176:179], v[200:203], v[18:21]
	v_mfma_f32_16x16x32_bf16 v[6:9], v[168:171], v[208:211], v[6:9]
	v_mfma_f32_16x16x32_bf16 v[2:5], v[176:179], v[208:211], v[2:5]
	s_setprio 0
	s_barrier
	s_add_i32 s78, 0, 0x18000
	s_add_i32 s79, 0, 0x1c000
	v_add_u32_e32 v160, s78, v251
	v_add_u32_e32 v176, s79, v251
	ds_read_b128 v[140:143], v160
	ds_read_b128 v[144:147], v160 offset:1024
	ds_read_b128 v[156:159], v160 offset:2048
	ds_read_b128 v[160:163], v160 offset:3072
	ds_read_b128 v[164:167], v176
	ds_read_b128 v[168:171], v176 offset:1024
	ds_read_b128 v[172:175], v176 offset:2048
	ds_read_b128 v[176:179], v176 offset:3072
	s_add_u32 s38, s72, 0xb0000
	s_addc_u32 s39, s73, 0
	s_mov_b32 m0, s52
	v_lshl_add_u64 v[216:217], s[38:39], 0, v[130:131]
	ds_read_b128 v[180:183], v253 offset:32768
	ds_read_b128 v[184:187], v253 offset:33792
	ds_read_b128 v[188:191], v253 offset:34816
	ds_read_b128 v[192:195], v253 offset:35840
	ds_read_b128 v[196:199], v253 offset:36864
	ds_read_b128 v[200:203], v253 offset:37888
	ds_read_b128 v[204:207], v253 offset:38912
	ds_read_b128 v[208:211], v253 offset:39936
	global_load_lds_dwordx4 v[216:217], off
	s_mov_b32 m0, s53
	v_lshl_add_u64 v[216:217], s[38:39], 0, v[132:133]
	global_load_lds_dwordx4 v[216:217], off
	s_waitcnt vmcnt(8) lgkmcnt(0)
	s_setprio 1
	s_barrier
	v_mfma_f32_16x16x32_bf16 v[126:129], v[140:143], v[180:183], v[126:129]
	v_mfma_f32_16x16x32_bf16 v[122:125], v[156:159], v[180:183], v[122:125]
	v_mfma_f32_16x16x32_bf16 v[110:113], v[140:143], v[188:191], v[110:113]
	v_mfma_f32_16x16x32_bf16 v[106:109], v[156:159], v[188:191], v[106:109]
	v_mfma_f32_16x16x32_bf16 v[94:97], v[140:143], v[196:199], v[94:97]
	v_mfma_f32_16x16x32_bf16 v[90:93], v[156:159], v[196:199], v[90:93]
	v_mfma_f32_16x16x32_bf16 v[78:81], v[140:143], v[204:207], v[78:81]
	v_mfma_f32_16x16x32_bf16 v[74:77], v[156:159], v[204:207], v[74:77]
	v_mfma_f32_16x16x32_bf16 v[126:129], v[144:147], v[184:187], v[126:129]
	v_mfma_f32_16x16x32_bf16 v[122:125], v[160:163], v[184:187], v[122:125]
	v_mfma_f32_16x16x32_bf16 v[110:113], v[144:147], v[192:195], v[110:113]
	v_mfma_f32_16x16x32_bf16 v[106:109], v[160:163], v[192:195], v[106:109]
	v_mfma_f32_16x16x32_bf16 v[94:97], v[144:147], v[200:203], v[94:97]
	v_mfma_f32_16x16x32_bf16 v[90:93], v[160:163], v[200:203], v[90:93]
	v_mfma_f32_16x16x32_bf16 v[78:81], v[144:147], v[208:211], v[78:81]
	v_mfma_f32_16x16x32_bf16 v[74:77], v[160:163], v[208:211], v[74:77]
	v_mfma_f32_16x16x32_bf16 v[118:121], v[164:167], v[180:183], v[118:121]
	v_mfma_f32_16x16x32_bf16 v[114:117], v[172:175], v[180:183], v[114:117]
	v_mfma_f32_16x16x32_bf16 v[102:105], v[164:167], v[188:191], v[102:105]
	v_mfma_f32_16x16x32_bf16 v[98:101], v[172:175], v[188:191], v[98:101]
	v_mfma_f32_16x16x32_bf16 v[86:89], v[164:167], v[196:199], v[86:89]
	v_mfma_f32_16x16x32_bf16 v[82:85], v[172:175], v[196:199], v[82:85]
	v_mfma_f32_16x16x32_bf16 v[70:73], v[164:167], v[204:207], v[70:73]
	v_mfma_f32_16x16x32_bf16 v[66:69], v[172:175], v[204:207], v[66:69]
	v_mfma_f32_16x16x32_bf16 v[118:121], v[168:171], v[184:187], v[118:121]
	v_mfma_f32_16x16x32_bf16 v[114:117], v[176:179], v[184:187], v[114:117]
	v_mfma_f32_16x16x32_bf16 v[102:105], v[168:171], v[192:195], v[102:105]
	v_mfma_f32_16x16x32_bf16 v[98:101], v[176:179], v[192:195], v[98:101]
	v_mfma_f32_16x16x32_bf16 v[86:89], v[168:171], v[200:203], v[86:89]
	v_mfma_f32_16x16x32_bf16 v[82:85], v[176:179], v[200:203], v[82:85]
	v_mfma_f32_16x16x32_bf16 v[70:73], v[168:171], v[208:211], v[70:73]
	v_mfma_f32_16x16x32_bf16 v[66:69], v[176:179], v[208:211], v[66:69]
	s_setprio 0
	s_barrier
	s_add_i32 s38, s78, s49
	v_lshl_add_u64 v[148:149], v[148:149], 0, s[70:71]
	s_mov_b32 m0, s38
	ds_read_b128 v[180:183], v253 offset:49152
	ds_read_b128 v[184:187], v253 offset:50176
	ds_read_b128 v[188:191], v253 offset:51200
	ds_read_b128 v[192:195], v253 offset:52224
	ds_read_b128 v[196:199], v253 offset:53248
	ds_read_b128 v[200:203], v253 offset:54272
	ds_read_b128 v[204:207], v253 offset:55296
	ds_read_b128 v[208:211], v253 offset:56320
	global_load_lds_dwordx4 v[148:149], off
	s_add_i32 m0, s38, 0x2000
	s_add_u32 s26, s26, 0xb0080
	v_lshl_add_u64 v[148:149], v[150:151], 0, s[70:71]
	s_addc_u32 s27, s27, 0
	s_add_i32 s38, s79, s49
	global_load_lds_dwordx4 v[148:149], off
	s_mov_b32 m0, s38
	v_lshl_add_u64 v[148:149], s[26:27], 0, v[0:1]
	global_load_lds_dwordx4 v[148:149], off
	s_add_i32 m0, s38, 0x2000
	v_lshl_add_u64 v[148:149], s[26:27], 0, v[134:135]
	global_load_lds_dwordx4 v[148:149], off
	s_mov_b32 m0, s74
	v_lshl_add_u64 v[148:149], v[212:213], 0, s[70:71]
	global_load_lds_dwordx4 v[148:149], off
	s_mov_b32 m0, s75
	v_lshl_add_u64 v[148:149], v[214:215], 0, s[70:71]
	global_load_lds_dwordx4 v[148:149], off
	s_waitcnt vmcnt(8) lgkmcnt(0)
	s_setprio 1
	s_barrier
	v_mfma_f32_16x16x32_bf16 v[62:65], v[140:143], v[180:183], v[62:65]
	v_mfma_f32_16x16x32_bf16 v[58:61], v[156:159], v[180:183], v[58:61]
	v_mfma_f32_16x16x32_bf16 v[46:49], v[140:143], v[188:191], v[46:49]
	v_mfma_f32_16x16x32_bf16 v[42:45], v[156:159], v[188:191], v[42:45]
	v_mfma_f32_16x16x32_bf16 v[30:33], v[140:143], v[196:199], v[30:33]
	v_mfma_f32_16x16x32_bf16 v[26:29], v[156:159], v[196:199], v[26:29]
	v_mfma_f32_16x16x32_bf16 v[14:17], v[140:143], v[204:207], v[14:17]
	v_mfma_f32_16x16x32_bf16 v[10:13], v[156:159], v[204:207], v[10:13]
	v_mfma_f32_16x16x32_bf16 v[62:65], v[144:147], v[184:187], v[62:65]
	v_mfma_f32_16x16x32_bf16 v[58:61], v[160:163], v[184:187], v[58:61]
	v_mfma_f32_16x16x32_bf16 v[46:49], v[144:147], v[192:195], v[46:49]
	v_mfma_f32_16x16x32_bf16 v[42:45], v[160:163], v[192:195], v[42:45]
	v_mfma_f32_16x16x32_bf16 v[30:33], v[144:147], v[200:203], v[30:33]
	v_mfma_f32_16x16x32_bf16 v[26:29], v[160:163], v[200:203], v[26:29]
	v_mfma_f32_16x16x32_bf16 v[14:17], v[144:147], v[208:211], v[14:17]
	v_mfma_f32_16x16x32_bf16 v[10:13], v[160:163], v[208:211], v[10:13]
	v_mfma_f32_16x16x32_bf16 v[54:57], v[164:167], v[180:183], v[54:57]
	v_mfma_f32_16x16x32_bf16 v[50:53], v[172:175], v[180:183], v[50:53]
	v_mfma_f32_16x16x32_bf16 v[38:41], v[164:167], v[188:191], v[38:41]
	v_mfma_f32_16x16x32_bf16 v[34:37], v[172:175], v[188:191], v[34:37]
	v_mfma_f32_16x16x32_bf16 v[22:25], v[164:167], v[196:199], v[22:25]
	v_mfma_f32_16x16x32_bf16 v[18:21], v[172:175], v[196:199], v[18:21]
	v_mfma_f32_16x16x32_bf16 v[6:9], v[164:167], v[204:207], v[6:9]
	v_mfma_f32_16x16x32_bf16 v[2:5], v[172:175], v[204:207], v[2:5]
	v_mfma_f32_16x16x32_bf16 v[54:57], v[168:171], v[184:187], v[54:57]
	v_mfma_f32_16x16x32_bf16 v[50:53], v[176:179], v[184:187], v[50:53]
	v_mfma_f32_16x16x32_bf16 v[38:41], v[168:171], v[192:195], v[38:41]
	v_mfma_f32_16x16x32_bf16 v[34:37], v[176:179], v[192:195], v[34:37]
	v_mfma_f32_16x16x32_bf16 v[22:25], v[168:171], v[200:203], v[22:25]
	v_mfma_f32_16x16x32_bf16 v[18:21], v[176:179], v[200:203], v[18:21]
	v_mfma_f32_16x16x32_bf16 v[6:9], v[168:171], v[208:211], v[6:9]
	v_mfma_f32_16x16x32_bf16 v[2:5], v[176:179], v[208:211], v[2:5]
	s_setprio 0
	s_barrier
	s_add_u32 vcc_lo, vcc_lo, 0x100
	s_addc_u32 vcc_hi, vcc_hi, 0
	s_cmp_ge_u32 s9, s28
	s_mov_b64 s[38:39], s[60:61]
	s_mov_b32 s26, s9
	s_cbranch_scc0 .LBB0_1000
	s_and_b64 vcc, exec, s[22:23]
	s_cbranch_vccz .LBB0_1003

.LBB0_1054:
	s_add_i32 s96, s26, 2
	s_add_u32 s36, s24, 0x100
	s_addc_u32 s37, s25, 0
	s_add_i32 s9, 0, 0x10000
	s_cmp_eq_u32 s93, s26
	s_cselect_b32 s39, s15, s37
	s_cselect_b32 s38, s14, s36
	v_add_u32_e32 v148, s9, v177
	s_cselect_b32 s27, s23, s95
	s_cselect_b32 s26, s22, s94
	s_add_i32 s78, 0, 0x14000
	ds_read_b128 v[140:143], v148
	ds_read_b128 v[144:147], v148 offset:1024
	ds_read_b128 v[156:159], v148 offset:2048
	ds_read_b128 v[160:163], v148 offset:3072
	v_add_u32_e32 v148, s78, v177
	ds_read_b128 v[164:167], v148
	ds_read_b128 v[168:171], v148 offset:1024
	ds_read_b128 v[172:175], v148 offset:2048
	ds_read_b128 v[180:183], v148 offset:3072
	v_lshl_add_u64 v[148:149], s[24:25], 0, v[136:137]
	s_add_i32 m0, s29, 0xc000
	ds_read_b128 v[184:187], v179
	ds_read_b128 v[188:191], v179 offset:1024
	ds_read_b128 v[192:195], v179 offset:2048
	ds_read_b128 v[196:199], v179 offset:3072
	ds_read_b128 v[200:203], v179 offset:4096
	ds_read_b128 v[204:207], v179 offset:5120
	ds_read_b128 v[208:211], v179 offset:6144
	ds_read_b128 v[212:215], v179 offset:7168
	global_load_lds_dwordx4 v[148:149], off
	s_add_i32 m0, s29, 0xe000
	v_lshl_add_u64 v[148:149], s[24:25], 0, v[138:139]
	global_load_lds_dwordx4 v[148:149], off
	s_waitcnt vmcnt(8) lgkmcnt(0)
	s_setprio 1
	s_barrier
	v_mfma_f32_16x16x32_bf16 v[126:129], v[140:143], v[184:187], v[126:129]
	v_mfma_f32_16x16x32_bf16 v[122:125], v[156:159], v[184:187], v[122:125]
	v_mfma_f32_16x16x32_bf16 v[110:113], v[140:143], v[192:195], v[110:113]
	v_mfma_f32_16x16x32_bf16 v[106:109], v[156:159], v[192:195], v[106:109]
	v_mfma_f32_16x16x32_bf16 v[94:97], v[140:143], v[200:203], v[94:97]
	v_mfma_f32_16x16x32_bf16 v[90:93], v[156:159], v[200:203], v[90:93]
	v_mfma_f32_16x16x32_bf16 v[78:81], v[140:143], v[208:211], v[78:81]
	v_mfma_f32_16x16x32_bf16 v[74:77], v[156:159], v[208:211], v[74:77]
	v_mfma_f32_16x16x32_bf16 v[126:129], v[144:147], v[188:191], v[126:129]
	v_mfma_f32_16x16x32_bf16 v[122:125], v[160:163], v[188:191], v[122:125]
	v_mfma_f32_16x16x32_bf16 v[110:113], v[144:147], v[196:199], v[110:113]
	v_mfma_f32_16x16x32_bf16 v[106:109], v[160:163], v[196:199], v[106:109]
	v_mfma_f32_16x16x32_bf16 v[94:97], v[144:147], v[204:207], v[94:97]
	v_mfma_f32_16x16x32_bf16 v[90:93], v[160:163], v[204:207], v[90:93]
	v_mfma_f32_16x16x32_bf16 v[78:81], v[144:147], v[212:215], v[78:81]
	v_mfma_f32_16x16x32_bf16 v[74:77], v[160:163], v[212:215], v[74:77]
	v_mfma_f32_16x16x32_bf16 v[118:121], v[164:167], v[184:187], v[118:121]
	v_mfma_f32_16x16x32_bf16 v[114:117], v[172:175], v[184:187], v[114:117]
	v_mfma_f32_16x16x32_bf16 v[102:105], v[164:167], v[192:195], v[102:105]
	v_mfma_f32_16x16x32_bf16 v[98:101], v[172:175], v[192:195], v[98:101]
	v_mfma_f32_16x16x32_bf16 v[86:89], v[164:167], v[200:203], v[86:89]
	v_mfma_f32_16x16x32_bf16 v[82:85], v[172:175], v[200:203], v[82:85]
	v_mfma_f32_16x16x32_bf16 v[70:73], v[164:167], v[208:211], v[70:73]
	v_mfma_f32_16x16x32_bf16 v[66:69], v[172:175], v[208:211], v[66:69]
	v_mfma_f32_16x16x32_bf16 v[118:121], v[168:171], v[188:191], v[118:121]
	v_mfma_f32_16x16x32_bf16 v[114:117], v[180:183], v[188:191], v[114:117]
	v_mfma_f32_16x16x32_bf16 v[102:105], v[168:171], v[196:199], v[102:105]
	v_mfma_f32_16x16x32_bf16 v[98:101], v[180:183], v[196:199], v[98:101]
	v_mfma_f32_16x16x32_bf16 v[86:89], v[168:171], v[204:207], v[86:89]
	v_mfma_f32_16x16x32_bf16 v[82:85], v[180:183], v[204:207], v[82:85]
	v_mfma_f32_16x16x32_bf16 v[70:73], v[168:171], v[212:215], v[70:73]
	v_mfma_f32_16x16x32_bf16 v[66:69], v[180:183], v[212:215], v[66:69]
	s_setprio 0
	s_barrier
	s_add_i32 s9, s9, s28
	v_lshl_add_u64 v[148:149], s[26:27], 0, v[0:1]
	s_mov_b32 m0, s9
	ds_read_b128 v[184:187], v179 offset:16384
	ds_read_b128 v[188:191], v179 offset:17408
	ds_read_b128 v[192:195], v179 offset:18432
	ds_read_b128 v[196:199], v179 offset:19456
	ds_read_b128 v[200:203], v179 offset:20480
	ds_read_b128 v[204:207], v179 offset:21504
	ds_read_b128 v[208:211], v179 offset:22528
	ds_read_b128 v[212:215], v179 offset:23552
	global_load_lds_dwordx4 v[148:149], off
	s_add_i32 m0, s9, 0x2000
	s_add_u32 s24, s26, 0xb0000
	v_lshl_add_u64 v[150:151], s[26:27], 0, v[134:135]
	s_addc_u32 s25, s27, 0
	s_add_i32 s9, s78, s28
	global_load_lds_dwordx4 v[150:151], off
	v_lshl_add_u64 v[216:217], s[24:25], 0, v[0:1]
	s_mov_b32 m0, s9
	v_lshl_add_u64 v[218:219], s[38:39], 0, v[132:133]
	global_load_lds_dwordx4 v[216:217], off
	s_add_i32 m0, s9, 0x2000
	v_lshl_add_u64 v[216:217], s[24:25], 0, v[134:135]
	global_load_lds_dwordx4 v[216:217], off
	s_mov_b32 m0, s29
	v_lshl_add_u64 v[216:217], s[38:39], 0, v[130:131]
	global_load_lds_dwordx4 v[216:217], off
	s_mov_b32 m0, s49
	s_nop 0
	global_load_lds_dwordx4 v[218:219], off
	s_waitcnt vmcnt(8) lgkmcnt(0)
	s_setprio 1
	s_barrier
	v_mfma_f32_16x16x32_bf16 v[62:65], v[140:143], v[184:187], v[62:65]
	v_mfma_f32_16x16x32_bf16 v[58:61], v[156:159], v[184:187], v[58:61]
	v_mfma_f32_16x16x32_bf16 v[46:49], v[140:143], v[192:195], v[46:49]
	v_mfma_f32_16x16x32_bf16 v[42:45], v[156:159], v[192:195], v[42:45]
	v_mfma_f32_16x16x32_bf16 v[30:33], v[140:143], v[200:203], v[30:33]
	v_mfma_f32_16x16x32_bf16 v[26:29], v[156:159], v[200:203], v[26:29]
	v_mfma_f32_16x16x32_bf16 v[14:17], v[140:143], v[208:211], v[14:17]
	v_mfma_f32_16x16x32_bf16 v[10:13], v[156:159], v[208:211], v[10:13]
	v_mfma_f32_16x16x32_bf16 v[62:65], v[144:147], v[188:191], v[62:65]
	v_mfma_f32_16x16x32_bf16 v[58:61], v[160:163], v[188:191], v[58:61]
	v_mfma_f32_16x16x32_bf16 v[46:49], v[144:147], v[196:199], v[46:49]
	v_mfma_f32_16x16x32_bf16 v[42:45], v[160:163], v[196:199], v[42:45]
	v_mfma_f32_16x16x32_bf16 v[30:33], v[144:147], v[204:207], v[30:33]
	v_mfma_f32_16x16x32_bf16 v[26:29], v[160:163], v[204:207], v[26:29]
	v_mfma_f32_16x16x32_bf16 v[14:17], v[144:147], v[212:215], v[14:17]
	v_mfma_f32_16x16x32_bf16 v[10:13], v[160:163], v[212:215], v[10:13]
	v_mfma_f32_16x16x32_bf16 v[54:57], v[164:167], v[184:187], v[54:57]
	v_mfma_f32_16x16x32_bf16 v[50:53], v[172:175], v[184:187], v[50:53]
	v_mfma_f32_16x16x32_bf16 v[38:41], v[164:167], v[192:195], v[38:41]
	v_mfma_f32_16x16x32_bf16 v[34:37], v[172:175], v[192:195], v[34:37]
	v_mfma_f32_16x16x32_bf16 v[22:25], v[164:167], v[200:203], v[22:25]
	v_mfma_f32_16x16x32_bf16 v[18:21], v[172:175], v[200:203], v[18:21]
	v_mfma_f32_16x16x32_bf16 v[6:9], v[164:167], v[208:211], v[6:9]
	v_mfma_f32_16x16x32_bf16 v[2:5], v[172:175], v[208:211], v[2:5]
	v_mfma_f32_16x16x32_bf16 v[54:57], v[168:171], v[188:191], v[54:57]
	v_mfma_f32_16x16x32_bf16 v[50:53], v[180:183], v[188:191], v[50:53]
	v_mfma_f32_16x16x32_bf16 v[38:41], v[168:171], v[196:199], v[38:41]
	v_mfma_f32_16x16x32_bf16 v[34:37], v[180:183], v[196:199], v[34:37]
	v_mfma_f32_16x16x32_bf16 v[22:25], v[168:171], v[204:207], v[22:25]
	v_mfma_f32_16x16x32_bf16 v[18:21], v[180:183], v[204:207], v[18:21]
	v_mfma_f32_16x16x32_bf16 v[6:9], v[168:171], v[212:215], v[6:9]
	v_mfma_f32_16x16x32_bf16 v[2:5], v[180:183], v[212:215], v[2:5]
	s_setprio 0
	s_barrier
	s_add_i32 s9, 0, 0x18000
	s_add_i32 s78, 0, 0x1c000
	v_add_u32_e32 v160, s9, v177
	v_add_u32_e32 v180, s78, v177
	ds_read_b128 v[140:143], v160
	ds_read_b128 v[144:147], v160 offset:1024
	ds_read_b128 v[156:159], v160 offset:2048
	ds_read_b128 v[160:163], v160 offset:3072
	ds_read_b128 v[164:167], v180
	ds_read_b128 v[168:171], v180 offset:1024
	ds_read_b128 v[172:175], v180 offset:2048
	ds_read_b128 v[180:183], v180 offset:3072
	s_add_u32 s24, s38, 0xb0000
	s_addc_u32 s25, s39, 0
	s_mov_b32 m0, s50
	v_lshl_add_u64 v[220:221], s[24:25], 0, v[130:131]
	ds_read_b128 v[184:187], v179 offset:32768
	ds_read_b128 v[188:191], v179 offset:33792
	ds_read_b128 v[192:195], v179 offset:34816
	ds_read_b128 v[196:199], v179 offset:35840
	ds_read_b128 v[200:203], v179 offset:36864
	ds_read_b128 v[204:207], v179 offset:37888
	ds_read_b128 v[208:211], v179 offset:38912
	ds_read_b128 v[212:215], v179 offset:39936
	global_load_lds_dwordx4 v[220:221], off
	s_mov_b32 m0, s51
	v_lshl_add_u64 v[220:221], s[24:25], 0, v[132:133]
	global_load_lds_dwordx4 v[220:221], off
	s_waitcnt vmcnt(8) lgkmcnt(0)
	s_setprio 1
	s_barrier
	v_mfma_f32_16x16x32_bf16 v[126:129], v[140:143], v[184:187], v[126:129]
	v_mfma_f32_16x16x32_bf16 v[122:125], v[156:159], v[184:187], v[122:125]
	v_mfma_f32_16x16x32_bf16 v[110:113], v[140:143], v[192:195], v[110:113]
	v_mfma_f32_16x16x32_bf16 v[106:109], v[156:159], v[192:195], v[106:109]
	v_mfma_f32_16x16x32_bf16 v[94:97], v[140:143], v[200:203], v[94:97]
	v_mfma_f32_16x16x32_bf16 v[90:93], v[156:159], v[200:203], v[90:93]
	v_mfma_f32_16x16x32_bf16 v[78:81], v[140:143], v[208:211], v[78:81]
	v_mfma_f32_16x16x32_bf16 v[74:77], v[156:159], v[208:211], v[74:77]
	v_mfma_f32_16x16x32_bf16 v[126:129], v[144:147], v[188:191], v[126:129]
	v_mfma_f32_16x16x32_bf16 v[122:125], v[160:163], v[188:191], v[122:125]
	v_mfma_f32_16x16x32_bf16 v[110:113], v[144:147], v[196:199], v[110:113]
	v_mfma_f32_16x16x32_bf16 v[106:109], v[160:163], v[196:199], v[106:109]
	v_mfma_f32_16x16x32_bf16 v[94:97], v[144:147], v[204:207], v[94:97]
	v_mfma_f32_16x16x32_bf16 v[90:93], v[160:163], v[204:207], v[90:93]
	v_mfma_f32_16x16x32_bf16 v[78:81], v[144:147], v[212:215], v[78:81]
	v_mfma_f32_16x16x32_bf16 v[74:77], v[160:163], v[212:215], v[74:77]
	v_mfma_f32_16x16x32_bf16 v[118:121], v[164:167], v[184:187], v[118:121]
	v_mfma_f32_16x16x32_bf16 v[114:117], v[172:175], v[184:187], v[114:117]
	v_mfma_f32_16x16x32_bf16 v[102:105], v[164:167], v[192:195], v[102:105]
	v_mfma_f32_16x16x32_bf16 v[98:101], v[172:175], v[192:195], v[98:101]
	v_mfma_f32_16x16x32_bf16 v[86:89], v[164:167], v[200:203], v[86:89]
	v_mfma_f32_16x16x32_bf16 v[82:85], v[172:175], v[200:203], v[82:85]
	v_mfma_f32_16x16x32_bf16 v[70:73], v[164:167], v[208:211], v[70:73]
	v_mfma_f32_16x16x32_bf16 v[66:69], v[172:175], v[208:211], v[66:69]
	v_mfma_f32_16x16x32_bf16 v[118:121], v[168:171], v[188:191], v[118:121]
	v_mfma_f32_16x16x32_bf16 v[114:117], v[180:183], v[188:191], v[114:117]
	v_mfma_f32_16x16x32_bf16 v[102:105], v[168:171], v[196:199], v[102:105]
	v_mfma_f32_16x16x32_bf16 v[98:101], v[180:183], v[196:199], v[98:101]
	v_mfma_f32_16x16x32_bf16 v[86:89], v[168:171], v[204:207], v[86:89]
	v_mfma_f32_16x16x32_bf16 v[82:85], v[180:183], v[204:207], v[82:85]
	v_mfma_f32_16x16x32_bf16 v[70:73], v[168:171], v[212:215], v[70:73]
	v_mfma_f32_16x16x32_bf16 v[66:69], v[180:183], v[212:215], v[66:69]
	s_setprio 0
	s_barrier
	s_add_i32 s9, s9, s28
	v_lshl_add_u64 v[148:149], v[148:149], 0, s[70:71]
	s_mov_b32 m0, s9
	ds_read_b128 v[184:187], v179 offset:49152
	ds_read_b128 v[188:191], v179 offset:50176
	ds_read_b128 v[192:195], v179 offset:51200
	ds_read_b128 v[196:199], v179 offset:52224
	ds_read_b128 v[200:203], v179 offset:53248
	ds_read_b128 v[204:207], v179 offset:54272
	ds_read_b128 v[208:211], v179 offset:55296
	ds_read_b128 v[212:215], v179 offset:56320
	global_load_lds_dwordx4 v[148:149], off
	s_add_i32 m0, s9, 0x2000
	s_add_u32 s24, s26, 0xb0080
	v_lshl_add_u64 v[148:149], v[150:151], 0, s[70:71]
	s_addc_u32 s25, s27, 0
	s_add_i32 s9, s78, s28
	global_load_lds_dwordx4 v[148:149], off
	s_mov_b32 m0, s9
	v_lshl_add_u64 v[148:149], s[24:25], 0, v[0:1]
	global_load_lds_dwordx4 v[148:149], off
	s_add_i32 m0, s9, 0x2000
	v_lshl_add_u64 v[148:149], s[24:25], 0, v[134:135]
	global_load_lds_dwordx4 v[148:149], off
	s_mov_b32 m0, s52
	v_lshl_add_u64 v[148:149], v[216:217], 0, s[70:71]
	global_load_lds_dwordx4 v[148:149], off
	s_mov_b32 m0, s53
	v_lshl_add_u64 v[148:149], v[218:219], 0, s[70:71]
	global_load_lds_dwordx4 v[148:149], off
	s_waitcnt vmcnt(8) lgkmcnt(0)
	s_setprio 1
	s_barrier
	v_mfma_f32_16x16x32_bf16 v[62:65], v[140:143], v[184:187], v[62:65]
	v_mfma_f32_16x16x32_bf16 v[58:61], v[156:159], v[184:187], v[58:61]
	v_mfma_f32_16x16x32_bf16 v[46:49], v[140:143], v[192:195], v[46:49]
	v_mfma_f32_16x16x32_bf16 v[42:45], v[156:159], v[192:195], v[42:45]
	v_mfma_f32_16x16x32_bf16 v[30:33], v[140:143], v[200:203], v[30:33]
	v_mfma_f32_16x16x32_bf16 v[26:29], v[156:159], v[200:203], v[26:29]
	v_mfma_f32_16x16x32_bf16 v[14:17], v[140:143], v[208:211], v[14:17]
	v_mfma_f32_16x16x32_bf16 v[10:13], v[156:159], v[208:211], v[10:13]
	v_mfma_f32_16x16x32_bf16 v[62:65], v[144:147], v[188:191], v[62:65]
	v_mfma_f32_16x16x32_bf16 v[58:61], v[160:163], v[188:191], v[58:61]
	v_mfma_f32_16x16x32_bf16 v[46:49], v[144:147], v[196:199], v[46:49]
	v_mfma_f32_16x16x32_bf16 v[42:45], v[160:163], v[196:199], v[42:45]
	v_mfma_f32_16x16x32_bf16 v[30:33], v[144:147], v[204:207], v[30:33]
	v_mfma_f32_16x16x32_bf16 v[26:29], v[160:163], v[204:207], v[26:29]
	v_mfma_f32_16x16x32_bf16 v[14:17], v[144:147], v[212:215], v[14:17]
	v_mfma_f32_16x16x32_bf16 v[10:13], v[160:163], v[212:215], v[10:13]
	v_mfma_f32_16x16x32_bf16 v[54:57], v[164:167], v[184:187], v[54:57]
	v_mfma_f32_16x16x32_bf16 v[50:53], v[172:175], v[184:187], v[50:53]
	v_mfma_f32_16x16x32_bf16 v[38:41], v[164:167], v[192:195], v[38:41]
	v_mfma_f32_16x16x32_bf16 v[34:37], v[172:175], v[192:195], v[34:37]
	v_mfma_f32_16x16x32_bf16 v[22:25], v[164:167], v[200:203], v[22:25]
	v_mfma_f32_16x16x32_bf16 v[18:21], v[172:175], v[200:203], v[18:21]
	v_mfma_f32_16x16x32_bf16 v[6:9], v[164:167], v[208:211], v[6:9]
	v_mfma_f32_16x16x32_bf16 v[2:5], v[172:175], v[208:211], v[2:5]
	v_mfma_f32_16x16x32_bf16 v[54:57], v[168:171], v[188:191], v[54:57]
	v_mfma_f32_16x16x32_bf16 v[50:53], v[180:183], v[188:191], v[50:53]
	v_mfma_f32_16x16x32_bf16 v[38:41], v[168:171], v[196:199], v[38:41]
	v_mfma_f32_16x16x32_bf16 v[34:37], v[180:183], v[196:199], v[34:37]
	v_mfma_f32_16x16x32_bf16 v[22:25], v[168:171], v[204:207], v[22:25]
	v_mfma_f32_16x16x32_bf16 v[18:21], v[180:183], v[204:207], v[18:21]
	v_mfma_f32_16x16x32_bf16 v[6:9], v[168:171], v[212:215], v[6:9]
	v_mfma_f32_16x16x32_bf16 v[2:5], v[180:183], v[212:215], v[2:5]
	s_setprio 0
	s_barrier
	s_add_u32 s94, s94, 0x100
	s_addc_u32 s95, s95, 0
	s_cmp_ge_u32 s96, s92
	s_mov_b64 s[24:25], s[36:37]
	s_mov_b32 s26, s96
	s_cbranch_scc0 .LBB0_1054
	s_and_b64 vcc, exec, s[12:13]
	s_cbranch_vccz .LBB0_1057
